# hyena filter gen: a3 tile loads lane-coalesced (64B segments per 4 lanes) + ds_bpermute into MFMA layout; 3-4 tiles in flight
# speedup vs baseline: 1.0641x; 1.0315x over previous
; __device__ __forceinline__ void phase_hyena(KP kp_, int hf){ asm volatile("" : "+s"(kp_)); const Params p=load_params(kp_);
;     ...
;       int n=lane&15, kg=lane>>4;
;       f16x8 bw0, bw1;
;       _Pragma("unroll") for (int e=0;e<8;++e){ bw0[e]=(n<4)?(_Float16)misc[(kg*8+e)*4+n]:(_Float16)0.f; bw1[e]=(n<4)?(_Float16)misc[(32+kg*8+e)*4+n]:(_Float16)0.f; }
;       const float dsc=-delta*(1.f/8191.f);
;       float pj0=__expf(dsc*(float)(kg*4)), pj1=__expf(dsc*(float)(kg*4+1)), pj2=__expf(dsc*(float)(kg*4+2)), pj3=__expf(dsc*(float)(kg*4+3));
;       float* Zf=(float*)Z; float ssl=0.f; int order=n&1; bool side1=(n&2)!=0;
;       _Pragma("unroll 8") for (int i=0;i<64;++i){ int tl=wid+8*i;
;         const _Float16* ap=a3+(size_t)(tl*16+n)*64+kg*8;
;         f16x8 a0=*(const f16x8*)ap, a1=*(const f16x8*)(ap+32);
;         f32x4 dd={0.f,0.f,0.f,0.f};
;         dd=__builtin_amdgcn_mfma_f32_16x16x32_f16(a0,bw0,dd,0,0,0);
;         dd=__builtin_amdgcn_mfma_f32_16x16x32_f16(a1,bw1,dd,0,0,0);
;         if (n<4){ float d0=__expf(dsc*(float)(tl*16)); int lag0=tl*16+kg*4;
;           float v0=dd[0]*d0*pj0, v1=dd[1]*d0*pj1, v2=dd[2]*d0*pj2, v3=dd[3]*d0*pj3;
;           if (!side1){ Zf[2*(lag0)+order]=v0; Zf[2*(lag0+1)+order]=v1; Zf[2*(lag0+2)+order]=v2; Zf[2*(lag0+3)+order]=v3; ssl+=v0*v0+v1*v1+v2*v2+v3*v3; }
;           else { if (lag0>=1){ Zf[2*(16384-lag0)+order]=v0; ssl+=v0*v0; }
;             Zf[2*(16384-lag0-1)+order]=v1; Zf[2*(16384-lag0-2)+order]=v2; Zf[2*(16384-lag0-3)+order]=v3; ssl+=v1*v1+v2*v2+v3*v3; } }
;       }
.LBB0_1232:
	s_or_b64 exec, exec, s[12:13]
	v_perm_b32 v3, v15, v3, s82
	v_perm_b32 v2, v7, v2, s82
	v_perm_b32 v1, v6, v1, s82
	v_perm_b32 v0, v5, v0, s82
	v_perm_b32 v7, v14, v13, s82
	v_perm_b32 v6, v12, v11, s82
	v_perm_b32 v5, v10, v9, s82
	v_perm_b32 v4, v8, v4, s82
	v_and_b32_e32 v222, 63, v154
	v_lshrrev_b32_e32 v29, 6, v154
	v_lshrrev_b32_e32 v223, 2, v222
	v_and_b32_e32 v224, 3, v222
	v_lshlrev_b32_e32 v85, 11, v29
	v_lshl_add_u32 v85, v223, 7, v85
	v_lshl_add_u32 v85, v224, 4, v85
	v_add_u32_e32 v85, 0x3b89000, v85
	global_load_dwordx4 v[228:231], v85, s[70:71]
	global_load_dwordx4 v[232:235], v85, s[70:71] offset:64
	v_add_u32_e32 v85, 0x4000, v85
	global_load_dwordx4 v[236:239], v85, s[70:71]
	global_load_dwordx4 v[240:243], v85, s[70:71] offset:64
	v_add_u32_e32 v85, 0x4000, v85
	global_load_dwordx4 v[244:247], v85, s[70:71]
	global_load_dwordx4 v[248:251], v85, s[70:71] offset:64
	v_add_u32_e32 v85, 0x4000, v85
	v_and_b32_e32 v223, 15, v222
	v_lshrrev_b32_e32 v224, 4, v222
	v_lshlrev_b32_e32 v30, 4, v223
	v_lshl_add_u32 v30, v224, 2, v30
	v_lshlrev_b32_e32 v78, 7, v29
	v_lshl_add_u32 v78, v224, 5, v78
	v_and_b32_e32 v227, 1, v223
	v_lshlrev_b32_e32 v227, 2, v227
	v_sub_u32_e32 v79, 0x1ffe8, v78
	v_add_u32_e32 v78, v78, v227
	v_add_u32_e32 v79, v79, v227
	v_cndmask_b32_e64 v78, v78, v79, s[40:41]
	v_mov_b32_e32 v227, 0x400
	v_mov_b32_e32 v79, 0xfffffc00
	v_cndmask_b32_e64 v79, v227, v79, s[40:41]
	v_cndmask_b32_e64 v80, v95, v50, s[40:41]
	v_cndmask_b32_e64 v81, v51, v96, s[40:41]
	v_cndmask_b32_e64 v82, v96, v51, s[40:41]
	v_cndmask_b32_e64 v84, v50, v95, s[40:41]
	v_lshrrev_b32_e32 v227, 4, v154
	v_cmp_eq_u32_e64 s[100:101], 0, v227
	s_nop 3
	s_and_b64 s[100:101], s[100:101], s[40:41]
	s_and_b64 s[100:101], s[100:101], s[38:39]
	s_andn2_b64 s[100:101], s[38:39], s[100:101]
	v_lshlrev_b32_e32 v29, 4, v29
	v_mov_b32_e32 v28, 0
	s_waitcnt vmcnt(4)
	ds_bpermute_b32 v12, v30, v228
	ds_bpermute_b32 v13, v30, v229
	ds_bpermute_b32 v14, v30, v230
	ds_bpermute_b32 v15, v30, v231
	ds_bpermute_b32 v16, v30, v232
	ds_bpermute_b32 v17, v30, v233
	ds_bpermute_b32 v18, v30, v234
	ds_bpermute_b32 v19, v30, v235
	global_load_dwordx4 v[228:231], v85, s[70:71]
	global_load_dwordx4 v[232:235], v85, s[70:71] offset:64
	v_add_u32_e32 v85, 0x4000, v85
	s_waitcnt vmcnt(4)
	ds_bpermute_b32 v20, v30, v236
	ds_bpermute_b32 v21, v30, v237
	ds_bpermute_b32 v22, v30, v238
	ds_bpermute_b32 v23, v30, v239
	ds_bpermute_b32 v24, v30, v240
	ds_bpermute_b32 v25, v30, v241
	ds_bpermute_b32 v26, v30, v242
	ds_bpermute_b32 v27, v30, v243
	global_load_dwordx4 v[236:239], v85, s[70:71]
	global_load_dwordx4 v[240:243], v85, s[70:71] offset:64
	v_add_u32_e32 v85, 0x4000, v85
	v_mov_b32_e32 v227, v29
	v_cvt_f32_i32_e32 v227, v227
	v_mul_f32_e32 v227, v93, v227
	v_mul_f32_e32 v227, 0x3fb8aa3b, v227
	v_exp_f32_e32 v226, v227
	s_waitcnt lgkmcnt(8)
	v_mfma_f32_16x16x32_f16 v[8:11], v[12:15], v[0:3], 0
	v_mfma_f32_16x16x32_f16 v[8:11], v[16:19], v[4:7], v[8:11]
	s_nop 7
	v_cndmask_b32_e64 v222, v8, v11, s[40:41]
	v_cndmask_b32_e64 v223, v9, v10, s[40:41]
	v_cndmask_b32_e64 v224, v10, v9, s[40:41]
	v_cndmask_b32_e64 v225, v11, v8, s[40:41]
	v_mul_f32_e32 v222, v222, v226
	v_mul_f32_e32 v223, v223, v226
	v_mul_f32_e32 v224, v224, v226
	v_mul_f32_e32 v225, v225, v226
	v_mul_f32_e32 v222, v80, v222
	v_mul_f32_e32 v223, v81, v223
	v_mul_f32_e32 v224, v82, v224
	v_mul_f32_e32 v225, v84, v225
	v_mul_f32_e32 v31, v222, v222
	v_fmac_f32_e32 v31, v223, v223
	v_fmac_f32_e32 v31, v224, v224
	v_cndmask_b32_e64 v227, 0, v225, s[100:101]
	v_fmac_f32_e32 v31, v227, v227
	v_add_f32_e32 v28, v28, v31
	s_mov_b64 exec, s[38:39]
	ds_write_b32 v78, v222
	ds_write_b32 v78, v223 offset:8
	ds_write_b32 v78, v224 offset:16
	s_mov_b64 exec, s[100:101]
	ds_write_b32 v78, v225 offset:24
	s_mov_b64 exec, -1
	v_add_u32_e32 v78, v78, v79
	s_waitcnt vmcnt(4)
	ds_bpermute_b32 v12, v30, v244
	ds_bpermute_b32 v13, v30, v245
	ds_bpermute_b32 v14, v30, v246
	ds_bpermute_b32 v15, v30, v247
	ds_bpermute_b32 v16, v30, v248
	ds_bpermute_b32 v17, v30, v249
	ds_bpermute_b32 v18, v30, v250
	ds_bpermute_b32 v19, v30, v251
	global_load_dwordx4 v[244:247], v85, s[70:71]
	global_load_dwordx4 v[248:251], v85, s[70:71] offset:64
	v_add_u32_e32 v85, 0x4000, v85
	v_add_u32_e32 v227, 0x80, v29
	v_cvt_f32_i32_e32 v227, v227
	v_mul_f32_e32 v227, v93, v227
	v_mul_f32_e32 v227, 0x3fb8aa3b, v227
	v_exp_f32_e32 v226, v227
	s_waitcnt lgkmcnt(12)
	v_mfma_f32_16x16x32_f16 v[8:11], v[20:23], v[0:3], 0
	v_mfma_f32_16x16x32_f16 v[8:11], v[24:27], v[4:7], v[8:11]
	s_nop 7
	v_cndmask_b32_e64 v222, v8, v11, s[40:41]
	v_cndmask_b32_e64 v223, v9, v10, s[40:41]
	v_cndmask_b32_e64 v224, v10, v9, s[40:41]
	v_cndmask_b32_e64 v225, v11, v8, s[40:41]
	v_mul_f32_e32 v222, v222, v226
	v_mul_f32_e32 v223, v223, v226
	v_mul_f32_e32 v224, v224, v226
	v_mul_f32_e32 v225, v225, v226
	v_mul_f32_e32 v222, v80, v222
	v_mul_f32_e32 v223, v81, v223
	v_mul_f32_e32 v224, v82, v224
	v_mul_f32_e32 v225, v84, v225
	v_mul_f32_e32 v31, v222, v222
	v_fmac_f32_e32 v31, v223, v223
	v_fmac_f32_e32 v31, v224, v224
	v_fmac_f32_e32 v31, v225, v225
	v_add_f32_e32 v28, v28, v31
	s_mov_b64 exec, s[38:39]
	ds_write_b32 v78, v222
	ds_write_b32 v78, v223 offset:8
	ds_write_b32 v78, v224 offset:16
	ds_write_b32 v78, v225 offset:24
	s_mov_b64 exec, -1
	v_add_u32_e32 v78, v78, v79
	s_waitcnt vmcnt(4)
; __device__ __forceinline__ void phase_hyena(KP kp_, int hf){ asm volatile("" : "+s"(kp_)); const Params p=load_params(kp_);
;     ...
;       _Pragma("unroll 8") for (int i=0;i<64;++i){ int tl=wid+8*i;
;         const _Float16* ap=a3+(size_t)(tl*16+n)*64+kg*8;
;         f16x8 a0=*(const f16x8*)ap, a1=*(const f16x8*)(ap+32);
;         f32x4 dd={0.f,0.f,0.f,0.f};
;         dd=__builtin_amdgcn_mfma_f32_16x16x32_f16(a0,bw0,dd,0,0,0);
;         dd=__builtin_amdgcn_mfma_f32_16x16x32_f16(a1,bw1,dd,0,0,0);
;         if (n<4){ float d0=__expf(dsc*(float)(tl*16)); int lag0=tl*16+kg*4;
;           float v0=dd[0]*d0*pj0, v1=dd[1]*d0*pj1, v2=dd[2]*d0*pj2, v3=dd[3]*d0*pj3;
;           if (!side1){ Zf[2*(lag0)+order]=v0; Zf[2*(lag0+1)+order]=v1; Zf[2*(lag0+2)+order]=v2; Zf[2*(lag0+3)+order]=v3; ssl+=v0*v0+v1*v1+v2*v2+v3*v3; }
;           else { if (lag0>=1){ Zf[2*(16384-lag0)+order]=v0; ssl+=v0*v0; }
;             Zf[2*(16384-lag0-1)+order]=v1; Zf[2*(16384-lag0-2)+order]=v2; Zf[2*(16384-lag0-3)+order]=v3; ssl+=v1*v1+v2*v2+v3*v3; } }
;       }
	ds_bpermute_b32 v20, v30, v228
	ds_bpermute_b32 v21, v30, v229
	ds_bpermute_b32 v22, v30, v230
	ds_bpermute_b32 v23, v30, v231
	ds_bpermute_b32 v24, v30, v232
	ds_bpermute_b32 v25, v30, v233
	ds_bpermute_b32 v26, v30, v234
	ds_bpermute_b32 v27, v30, v235
	global_load_dwordx4 v[228:231], v85, s[70:71]
	global_load_dwordx4 v[232:235], v85, s[70:71] offset:64
	v_add_u32_e32 v85, 0x4000, v85
	v_add_u32_e32 v227, 0x100, v29
	v_cvt_f32_i32_e32 v227, v227
	v_mul_f32_e32 v227, v93, v227
	v_mul_f32_e32 v227, 0x3fb8aa3b, v227
	v_exp_f32_e32 v226, v227
	s_waitcnt lgkmcnt(12)
	v_mfma_f32_16x16x32_f16 v[8:11], v[12:15], v[0:3], 0
	v_mfma_f32_16x16x32_f16 v[8:11], v[16:19], v[4:7], v[8:11]
	s_nop 7
	v_cndmask_b32_e64 v222, v8, v11, s[40:41]
	v_cndmask_b32_e64 v223, v9, v10, s[40:41]
	v_cndmask_b32_e64 v224, v10, v9, s[40:41]
	v_cndmask_b32_e64 v225, v11, v8, s[40:41]
	v_mul_f32_e32 v222, v222, v226
	v_mul_f32_e32 v223, v223, v226
	v_mul_f32_e32 v224, v224, v226
	v_mul_f32_e32 v225, v225, v226
	v_mul_f32_e32 v222, v80, v222
	v_mul_f32_e32 v223, v81, v223
	v_mul_f32_e32 v224, v82, v224
	v_mul_f32_e32 v225, v84, v225
	v_mul_f32_e32 v31, v222, v222
	v_fmac_f32_e32 v31, v223, v223
	v_fmac_f32_e32 v31, v224, v224
	v_fmac_f32_e32 v31, v225, v225
	v_add_f32_e32 v28, v28, v31
	s_mov_b64 exec, s[38:39]
	ds_write_b32 v78, v222
	ds_write_b32 v78, v223 offset:8
	ds_write_b32 v78, v224 offset:16
	ds_write_b32 v78, v225 offset:24
	s_mov_b64 exec, -1
	v_add_u32_e32 v78, v78, v79
	s_waitcnt vmcnt(4)
	ds_bpermute_b32 v12, v30, v236
	ds_bpermute_b32 v13, v30, v237
	ds_bpermute_b32 v14, v30, v238
	ds_bpermute_b32 v15, v30, v239
	ds_bpermute_b32 v16, v30, v240
	ds_bpermute_b32 v17, v30, v241
	ds_bpermute_b32 v18, v30, v242
	ds_bpermute_b32 v19, v30, v243
	global_load_dwordx4 v[236:239], v85, s[70:71]
	global_load_dwordx4 v[240:243], v85, s[70:71] offset:64
	v_add_u32_e32 v85, 0x4000, v85
	v_add_u32_e32 v227, 0x180, v29
	v_cvt_f32_i32_e32 v227, v227
	v_mul_f32_e32 v227, v93, v227
	v_mul_f32_e32 v227, 0x3fb8aa3b, v227
	v_exp_f32_e32 v226, v227
	s_waitcnt lgkmcnt(12)
	v_mfma_f32_16x16x32_f16 v[8:11], v[20:23], v[0:3], 0
	v_mfma_f32_16x16x32_f16 v[8:11], v[24:27], v[4:7], v[8:11]
	s_nop 7
	v_cndmask_b32_e64 v222, v8, v11, s[40:41]
	v_cndmask_b32_e64 v223, v9, v10, s[40:41]
	v_cndmask_b32_e64 v224, v10, v9, s[40:41]
	v_cndmask_b32_e64 v225, v11, v8, s[40:41]
	v_mul_f32_e32 v222, v222, v226
	v_mul_f32_e32 v223, v223, v226
	v_mul_f32_e32 v224, v224, v226
	v_mul_f32_e32 v225, v225, v226
	v_mul_f32_e32 v222, v80, v222
	v_mul_f32_e32 v223, v81, v223
	v_mul_f32_e32 v224, v82, v224
	v_mul_f32_e32 v225, v84, v225
	v_mul_f32_e32 v31, v222, v222
	v_fmac_f32_e32 v31, v223, v223
	v_fmac_f32_e32 v31, v224, v224
	v_fmac_f32_e32 v31, v225, v225
	v_add_f32_e32 v28, v28, v31
	s_mov_b64 exec, s[38:39]
	ds_write_b32 v78, v222
	ds_write_b32 v78, v223 offset:8
	ds_write_b32 v78, v224 offset:16
	ds_write_b32 v78, v225 offset:24
	s_mov_b64 exec, -1
	v_add_u32_e32 v78, v78, v79
	s_waitcnt vmcnt(4)
	ds_bpermute_b32 v20, v30, v244
	ds_bpermute_b32 v21, v30, v245
	ds_bpermute_b32 v22, v30, v246
	ds_bpermute_b32 v23, v30, v247
	ds_bpermute_b32 v24, v30, v248
	ds_bpermute_b32 v25, v30, v249
	ds_bpermute_b32 v26, v30, v250
	ds_bpermute_b32 v27, v30, v251
	global_load_dwordx4 v[244:247], v85, s[70:71]
	global_load_dwordx4 v[248:251], v85, s[70:71] offset:64
	v_add_u32_e32 v85, 0x4000, v85
	v_add_u32_e32 v227, 0x200, v29
	v_cvt_f32_i32_e32 v227, v227
	v_mul_f32_e32 v227, v93, v227
	v_mul_f32_e32 v227, 0x3fb8aa3b, v227
	v_exp_f32_e32 v226, v227
	s_waitcnt lgkmcnt(12)
	v_mfma_f32_16x16x32_f16 v[8:11], v[12:15], v[0:3], 0
	v_mfma_f32_16x16x32_f16 v[8:11], v[16:19], v[4:7], v[8:11]
	s_nop 7
	v_cndmask_b32_e64 v222, v8, v11, s[40:41]
	v_cndmask_b32_e64 v223, v9, v10, s[40:41]
	v_cndmask_b32_e64 v224, v10, v9, s[40:41]
	v_cndmask_b32_e64 v225, v11, v8, s[40:41]
	v_mul_f32_e32 v222, v222, v226
	v_mul_f32_e32 v223, v223, v226
	v_mul_f32_e32 v224, v224, v226
	v_mul_f32_e32 v225, v225, v226
	v_mul_f32_e32 v222, v80, v222
	v_mul_f32_e32 v223, v81, v223
	v_mul_f32_e32 v224, v82, v224
	v_mul_f32_e32 v225, v84, v225
	v_mul_f32_e32 v31, v222, v222
	v_fmac_f32_e32 v31, v223, v223
	v_fmac_f32_e32 v31, v224, v224
	v_fmac_f32_e32 v31, v225, v225
	v_add_f32_e32 v28, v28, v31
	s_mov_b64 exec, s[38:39]
	ds_write_b32 v78, v222
	ds_write_b32 v78, v223 offset:8
	ds_write_b32 v78, v224 offset:16
	ds_write_b32 v78, v225 offset:24
	s_mov_b64 exec, -1
	v_add_u32_e32 v78, v78, v79
	s_waitcnt vmcnt(4)
	ds_bpermute_b32 v12, v30, v228
	ds_bpermute_b32 v13, v30, v229
	ds_bpermute_b32 v14, v30, v230
	ds_bpermute_b32 v15, v30, v231
	ds_bpermute_b32 v16, v30, v232
	ds_bpermute_b32 v17, v30, v233
	ds_bpermute_b32 v18, v30, v234
	ds_bpermute_b32 v19, v30, v235
	global_load_dwordx4 v[228:231], v85, s[70:71]
	global_load_dwordx4 v[232:235], v85, s[70:71] offset:64
	v_add_u32_e32 v85, 0x4000, v85
	v_add_u32_e32 v227, 0x280, v29
	v_cvt_f32_i32_e32 v227, v227
	v_mul_f32_e32 v227, v93, v227
	v_mul_f32_e32 v227, 0x3fb8aa3b, v227
	v_exp_f32_e32 v226, v227
	s_waitcnt lgkmcnt(12)
	v_mfma_f32_16x16x32_f16 v[8:11], v[20:23], v[0:3], 0
	v_mfma_f32_16x16x32_f16 v[8:11], v[24:27], v[4:7], v[8:11]
	s_nop 7
	v_cndmask_b32_e64 v222, v8, v11, s[40:41]
	v_cndmask_b32_e64 v223, v9, v10, s[40:41]
	v_cndmask_b32_e64 v224, v10, v9, s[40:41]
	v_cndmask_b32_e64 v225, v11, v8, s[40:41]
	v_mul_f32_e32 v222, v222, v226
	v_mul_f32_e32 v223, v223, v226
	v_mul_f32_e32 v224, v224, v226
	v_mul_f32_e32 v225, v225, v226
	v_mul_f32_e32 v222, v80, v222
	v_mul_f32_e32 v223, v81, v223
	v_mul_f32_e32 v224, v82, v224
	v_mul_f32_e32 v225, v84, v225
	v_mul_f32_e32 v31, v222, v222
	v_fmac_f32_e32 v31, v223, v223
	v_fmac_f32_e32 v31, v224, v224
	v_fmac_f32_e32 v31, v225, v225
	v_add_f32_e32 v28, v28, v31
	s_mov_b64 exec, s[38:39]
	ds_write_b32 v78, v222
	ds_write_b32 v78, v223 offset:8
	ds_write_b32 v78, v224 offset:16
	ds_write_b32 v78, v225 offset:24
	s_mov_b64 exec, -1
	v_add_u32_e32 v78, v78, v79
	s_waitcnt vmcnt(4)
; __device__ __forceinline__ void phase_hyena(KP kp_, int hf){ asm volatile("" : "+s"(kp_)); const Params p=load_params(kp_);
;     ...
;       _Pragma("unroll 8") for (int i=0;i<64;++i){ int tl=wid+8*i;
;         const _Float16* ap=a3+(size_t)(tl*16+n)*64+kg*8;
;         f16x8 a0=*(const f16x8*)ap, a1=*(const f16x8*)(ap+32);
;         f32x4 dd={0.f,0.f,0.f,0.f};
;         dd=__builtin_amdgcn_mfma_f32_16x16x32_f16(a0,bw0,dd,0,0,0);
;         dd=__builtin_amdgcn_mfma_f32_16x16x32_f16(a1,bw1,dd,0,0,0);
;         if (n<4){ float d0=__expf(dsc*(float)(tl*16)); int lag0=tl*16+kg*4;
;           float v0=dd[0]*d0*pj0, v1=dd[1]*d0*pj1, v2=dd[2]*d0*pj2, v3=dd[3]*d0*pj3;
;           if (!side1){ Zf[2*(lag0)+order]=v0; Zf[2*(lag0+1)+order]=v1; Zf[2*(lag0+2)+order]=v2; Zf[2*(lag0+3)+order]=v3; ssl+=v0*v0+v1*v1+v2*v2+v3*v3; }
;           else { if (lag0>=1){ Zf[2*(16384-lag0)+order]=v0; ssl+=v0*v0; }
;             Zf[2*(16384-lag0-1)+order]=v1; Zf[2*(16384-lag0-2)+order]=v2; Zf[2*(16384-lag0-3)+order]=v3; ssl+=v1*v1+v2*v2+v3*v3; } }
;       }
	ds_bpermute_b32 v20, v30, v236
	ds_bpermute_b32 v21, v30, v237
	ds_bpermute_b32 v22, v30, v238
	ds_bpermute_b32 v23, v30, v239
	ds_bpermute_b32 v24, v30, v240
	ds_bpermute_b32 v25, v30, v241
	ds_bpermute_b32 v26, v30, v242
	ds_bpermute_b32 v27, v30, v243
	global_load_dwordx4 v[236:239], v85, s[70:71]
	global_load_dwordx4 v[240:243], v85, s[70:71] offset:64
	v_add_u32_e32 v85, 0x4000, v85
	v_add_u32_e32 v227, 0x300, v29
	v_cvt_f32_i32_e32 v227, v227
	v_mul_f32_e32 v227, v93, v227
	v_mul_f32_e32 v227, 0x3fb8aa3b, v227
	v_exp_f32_e32 v226, v227
	s_waitcnt lgkmcnt(12)
	v_mfma_f32_16x16x32_f16 v[8:11], v[12:15], v[0:3], 0
	v_mfma_f32_16x16x32_f16 v[8:11], v[16:19], v[4:7], v[8:11]
	s_nop 7
	v_cndmask_b32_e64 v222, v8, v11, s[40:41]
	v_cndmask_b32_e64 v223, v9, v10, s[40:41]
	v_cndmask_b32_e64 v224, v10, v9, s[40:41]
	v_cndmask_b32_e64 v225, v11, v8, s[40:41]
	v_mul_f32_e32 v222, v222, v226
	v_mul_f32_e32 v223, v223, v226
	v_mul_f32_e32 v224, v224, v226
	v_mul_f32_e32 v225, v225, v226
	v_mul_f32_e32 v222, v80, v222
	v_mul_f32_e32 v223, v81, v223
	v_mul_f32_e32 v224, v82, v224
	v_mul_f32_e32 v225, v84, v225
	v_mul_f32_e32 v31, v222, v222
	v_fmac_f32_e32 v31, v223, v223
	v_fmac_f32_e32 v31, v224, v224
	v_fmac_f32_e32 v31, v225, v225
	v_add_f32_e32 v28, v28, v31
	s_mov_b64 exec, s[38:39]
	ds_write_b32 v78, v222
	ds_write_b32 v78, v223 offset:8
	ds_write_b32 v78, v224 offset:16
	ds_write_b32 v78, v225 offset:24
	s_mov_b64 exec, -1
	v_add_u32_e32 v78, v78, v79
	s_waitcnt vmcnt(4)
	ds_bpermute_b32 v12, v30, v244
	ds_bpermute_b32 v13, v30, v245
	ds_bpermute_b32 v14, v30, v246
	ds_bpermute_b32 v15, v30, v247
	ds_bpermute_b32 v16, v30, v248
	ds_bpermute_b32 v17, v30, v249
	ds_bpermute_b32 v18, v30, v250
	ds_bpermute_b32 v19, v30, v251
	global_load_dwordx4 v[244:247], v85, s[70:71]
	global_load_dwordx4 v[248:251], v85, s[70:71] offset:64
	v_add_u32_e32 v85, 0x4000, v85
	v_add_u32_e32 v227, 0x380, v29
	v_cvt_f32_i32_e32 v227, v227
	v_mul_f32_e32 v227, v93, v227
	v_mul_f32_e32 v227, 0x3fb8aa3b, v227
	v_exp_f32_e32 v226, v227
	s_waitcnt lgkmcnt(12)
	v_mfma_f32_16x16x32_f16 v[8:11], v[20:23], v[0:3], 0
	v_mfma_f32_16x16x32_f16 v[8:11], v[24:27], v[4:7], v[8:11]
	s_nop 7
	v_cndmask_b32_e64 v222, v8, v11, s[40:41]
	v_cndmask_b32_e64 v223, v9, v10, s[40:41]
	v_cndmask_b32_e64 v224, v10, v9, s[40:41]
	v_cndmask_b32_e64 v225, v11, v8, s[40:41]
	v_mul_f32_e32 v222, v222, v226
	v_mul_f32_e32 v223, v223, v226
	v_mul_f32_e32 v224, v224, v226
	v_mul_f32_e32 v225, v225, v226
	v_mul_f32_e32 v222, v80, v222
	v_mul_f32_e32 v223, v81, v223
	v_mul_f32_e32 v224, v82, v224
	v_mul_f32_e32 v225, v84, v225
	v_mul_f32_e32 v31, v222, v222
	v_fmac_f32_e32 v31, v223, v223
	v_fmac_f32_e32 v31, v224, v224
	v_fmac_f32_e32 v31, v225, v225
	v_add_f32_e32 v28, v28, v31
	s_mov_b64 exec, s[38:39]
	ds_write_b32 v78, v222
	ds_write_b32 v78, v223 offset:8
	ds_write_b32 v78, v224 offset:16
	ds_write_b32 v78, v225 offset:24
	s_mov_b64 exec, -1
	v_add_u32_e32 v78, v78, v79
	s_waitcnt vmcnt(4)
	ds_bpermute_b32 v20, v30, v228
	ds_bpermute_b32 v21, v30, v229
	ds_bpermute_b32 v22, v30, v230
	ds_bpermute_b32 v23, v30, v231
	ds_bpermute_b32 v24, v30, v232
	ds_bpermute_b32 v25, v30, v233
	ds_bpermute_b32 v26, v30, v234
	ds_bpermute_b32 v27, v30, v235
	global_load_dwordx4 v[228:231], v85, s[70:71]
	global_load_dwordx4 v[232:235], v85, s[70:71] offset:64
	v_add_u32_e32 v85, 0x4000, v85
	v_add_u32_e32 v227, 0x400, v29
	v_cvt_f32_i32_e32 v227, v227
	v_mul_f32_e32 v227, v93, v227
	v_mul_f32_e32 v227, 0x3fb8aa3b, v227
	v_exp_f32_e32 v226, v227
	s_waitcnt lgkmcnt(12)
	v_mfma_f32_16x16x32_f16 v[8:11], v[12:15], v[0:3], 0
	v_mfma_f32_16x16x32_f16 v[8:11], v[16:19], v[4:7], v[8:11]
	s_nop 7
	v_cndmask_b32_e64 v222, v8, v11, s[40:41]
	v_cndmask_b32_e64 v223, v9, v10, s[40:41]
	v_cndmask_b32_e64 v224, v10, v9, s[40:41]
	v_cndmask_b32_e64 v225, v11, v8, s[40:41]
	v_mul_f32_e32 v222, v222, v226
	v_mul_f32_e32 v223, v223, v226
	v_mul_f32_e32 v224, v224, v226
	v_mul_f32_e32 v225, v225, v226
	v_mul_f32_e32 v222, v80, v222
	v_mul_f32_e32 v223, v81, v223
	v_mul_f32_e32 v224, v82, v224
	v_mul_f32_e32 v225, v84, v225
	v_mul_f32_e32 v31, v222, v222
	v_fmac_f32_e32 v31, v223, v223
	v_fmac_f32_e32 v31, v224, v224
	v_fmac_f32_e32 v31, v225, v225
	v_add_f32_e32 v28, v28, v31
	s_mov_b64 exec, s[38:39]
	ds_write_b32 v78, v222
	ds_write_b32 v78, v223 offset:8
	ds_write_b32 v78, v224 offset:16
	ds_write_b32 v78, v225 offset:24
	s_mov_b64 exec, -1
	v_add_u32_e32 v78, v78, v79
	s_waitcnt vmcnt(4)
	ds_bpermute_b32 v12, v30, v236
	ds_bpermute_b32 v13, v30, v237
	ds_bpermute_b32 v14, v30, v238
	ds_bpermute_b32 v15, v30, v239
	ds_bpermute_b32 v16, v30, v240
	ds_bpermute_b32 v17, v30, v241
	ds_bpermute_b32 v18, v30, v242
	ds_bpermute_b32 v19, v30, v243
	global_load_dwordx4 v[236:239], v85, s[70:71]
	global_load_dwordx4 v[240:243], v85, s[70:71] offset:64
	v_add_u32_e32 v85, 0x4000, v85
	v_add_u32_e32 v227, 0x480, v29
	v_cvt_f32_i32_e32 v227, v227
	v_mul_f32_e32 v227, v93, v227
	v_mul_f32_e32 v227, 0x3fb8aa3b, v227
	v_exp_f32_e32 v226, v227
	s_waitcnt lgkmcnt(12)
	v_mfma_f32_16x16x32_f16 v[8:11], v[20:23], v[0:3], 0
	v_mfma_f32_16x16x32_f16 v[8:11], v[24:27], v[4:7], v[8:11]
	s_nop 7
	v_cndmask_b32_e64 v222, v8, v11, s[40:41]
	v_cndmask_b32_e64 v223, v9, v10, s[40:41]
	v_cndmask_b32_e64 v224, v10, v9, s[40:41]
	v_cndmask_b32_e64 v225, v11, v8, s[40:41]
	v_mul_f32_e32 v222, v222, v226
	v_mul_f32_e32 v223, v223, v226
	v_mul_f32_e32 v224, v224, v226
	v_mul_f32_e32 v225, v225, v226
	v_mul_f32_e32 v222, v80, v222
	v_mul_f32_e32 v223, v81, v223
	v_mul_f32_e32 v224, v82, v224
	v_mul_f32_e32 v225, v84, v225
	v_mul_f32_e32 v31, v222, v222
	v_fmac_f32_e32 v31, v223, v223
	v_fmac_f32_e32 v31, v224, v224
	v_fmac_f32_e32 v31, v225, v225
	v_add_f32_e32 v28, v28, v31
	s_mov_b64 exec, s[38:39]
	ds_write_b32 v78, v222
	ds_write_b32 v78, v223 offset:8
	ds_write_b32 v78, v224 offset:16
	ds_write_b32 v78, v225 offset:24
	s_mov_b64 exec, -1
	v_add_u32_e32 v78, v78, v79
	s_waitcnt vmcnt(4)
; __device__ __forceinline__ void phase_hyena(KP kp_, int hf){ asm volatile("" : "+s"(kp_)); const Params p=load_params(kp_);
;     ...
;       _Pragma("unroll 8") for (int i=0;i<64;++i){ int tl=wid+8*i;
;         const _Float16* ap=a3+(size_t)(tl*16+n)*64+kg*8;
;         f16x8 a0=*(const f16x8*)ap, a1=*(const f16x8*)(ap+32);
;         f32x4 dd={0.f,0.f,0.f,0.f};
;         dd=__builtin_amdgcn_mfma_f32_16x16x32_f16(a0,bw0,dd,0,0,0);
;         dd=__builtin_amdgcn_mfma_f32_16x16x32_f16(a1,bw1,dd,0,0,0);
;         if (n<4){ float d0=__expf(dsc*(float)(tl*16)); int lag0=tl*16+kg*4;
;           float v0=dd[0]*d0*pj0, v1=dd[1]*d0*pj1, v2=dd[2]*d0*pj2, v3=dd[3]*d0*pj3;
;           if (!side1){ Zf[2*(lag0)+order]=v0; Zf[2*(lag0+1)+order]=v1; Zf[2*(lag0+2)+order]=v2; Zf[2*(lag0+3)+order]=v3; ssl+=v0*v0+v1*v1+v2*v2+v3*v3; }
;           else { if (lag0>=1){ Zf[2*(16384-lag0)+order]=v0; ssl+=v0*v0; }
;             Zf[2*(16384-lag0-1)+order]=v1; Zf[2*(16384-lag0-2)+order]=v2; Zf[2*(16384-lag0-3)+order]=v3; ssl+=v1*v1+v2*v2+v3*v3; } }
;       }
	ds_bpermute_b32 v20, v30, v244
	ds_bpermute_b32 v21, v30, v245
	ds_bpermute_b32 v22, v30, v246
	ds_bpermute_b32 v23, v30, v247
	ds_bpermute_b32 v24, v30, v248
	ds_bpermute_b32 v25, v30, v249
	ds_bpermute_b32 v26, v30, v250
	ds_bpermute_b32 v27, v30, v251
	global_load_dwordx4 v[244:247], v85, s[70:71]
	global_load_dwordx4 v[248:251], v85, s[70:71] offset:64
	v_add_u32_e32 v85, 0x4000, v85
	v_add_u32_e32 v227, 0x500, v29
	v_cvt_f32_i32_e32 v227, v227
	v_mul_f32_e32 v227, v93, v227
	v_mul_f32_e32 v227, 0x3fb8aa3b, v227
	v_exp_f32_e32 v226, v227
	s_waitcnt lgkmcnt(12)
	v_mfma_f32_16x16x32_f16 v[8:11], v[12:15], v[0:3], 0
	v_mfma_f32_16x16x32_f16 v[8:11], v[16:19], v[4:7], v[8:11]
	s_nop 7
	v_cndmask_b32_e64 v222, v8, v11, s[40:41]
	v_cndmask_b32_e64 v223, v9, v10, s[40:41]
	v_cndmask_b32_e64 v224, v10, v9, s[40:41]
	v_cndmask_b32_e64 v225, v11, v8, s[40:41]
	v_mul_f32_e32 v222, v222, v226
	v_mul_f32_e32 v223, v223, v226
	v_mul_f32_e32 v224, v224, v226
	v_mul_f32_e32 v225, v225, v226
	v_mul_f32_e32 v222, v80, v222
	v_mul_f32_e32 v223, v81, v223
	v_mul_f32_e32 v224, v82, v224
	v_mul_f32_e32 v225, v84, v225
	v_mul_f32_e32 v31, v222, v222
	v_fmac_f32_e32 v31, v223, v223
	v_fmac_f32_e32 v31, v224, v224
	v_fmac_f32_e32 v31, v225, v225
	v_add_f32_e32 v28, v28, v31
	s_mov_b64 exec, s[38:39]
	ds_write_b32 v78, v222
	ds_write_b32 v78, v223 offset:8
	ds_write_b32 v78, v224 offset:16
	ds_write_b32 v78, v225 offset:24
	s_mov_b64 exec, -1
	v_add_u32_e32 v78, v78, v79
	s_waitcnt vmcnt(4)
	ds_bpermute_b32 v12, v30, v228
	ds_bpermute_b32 v13, v30, v229
	ds_bpermute_b32 v14, v30, v230
	ds_bpermute_b32 v15, v30, v231
	ds_bpermute_b32 v16, v30, v232
	ds_bpermute_b32 v17, v30, v233
	ds_bpermute_b32 v18, v30, v234
	ds_bpermute_b32 v19, v30, v235
	global_load_dwordx4 v[228:231], v85, s[70:71]
	global_load_dwordx4 v[232:235], v85, s[70:71] offset:64
	v_add_u32_e32 v85, 0x4000, v85
	v_add_u32_e32 v227, 0x580, v29
	v_cvt_f32_i32_e32 v227, v227
	v_mul_f32_e32 v227, v93, v227
	v_mul_f32_e32 v227, 0x3fb8aa3b, v227
	v_exp_f32_e32 v226, v227
	s_waitcnt lgkmcnt(12)
	v_mfma_f32_16x16x32_f16 v[8:11], v[20:23], v[0:3], 0
	v_mfma_f32_16x16x32_f16 v[8:11], v[24:27], v[4:7], v[8:11]
	s_nop 7
	v_cndmask_b32_e64 v222, v8, v11, s[40:41]
	v_cndmask_b32_e64 v223, v9, v10, s[40:41]
	v_cndmask_b32_e64 v224, v10, v9, s[40:41]
	v_cndmask_b32_e64 v225, v11, v8, s[40:41]
	v_mul_f32_e32 v222, v222, v226
	v_mul_f32_e32 v223, v223, v226
	v_mul_f32_e32 v224, v224, v226
	v_mul_f32_e32 v225, v225, v226
	v_mul_f32_e32 v222, v80, v222
	v_mul_f32_e32 v223, v81, v223
	v_mul_f32_e32 v224, v82, v224
	v_mul_f32_e32 v225, v84, v225
	v_mul_f32_e32 v31, v222, v222
	v_fmac_f32_e32 v31, v223, v223
	v_fmac_f32_e32 v31, v224, v224
	v_fmac_f32_e32 v31, v225, v225
	v_add_f32_e32 v28, v28, v31
	s_mov_b64 exec, s[38:39]
	ds_write_b32 v78, v222
	ds_write_b32 v78, v223 offset:8
	ds_write_b32 v78, v224 offset:16
	ds_write_b32 v78, v225 offset:24
	s_mov_b64 exec, -1
	v_add_u32_e32 v78, v78, v79
	s_waitcnt vmcnt(4)
	ds_bpermute_b32 v20, v30, v236
	ds_bpermute_b32 v21, v30, v237
	ds_bpermute_b32 v22, v30, v238
	ds_bpermute_b32 v23, v30, v239
	ds_bpermute_b32 v24, v30, v240
	ds_bpermute_b32 v25, v30, v241
	ds_bpermute_b32 v26, v30, v242
	ds_bpermute_b32 v27, v30, v243
	global_load_dwordx4 v[236:239], v85, s[70:71]
	global_load_dwordx4 v[240:243], v85, s[70:71] offset:64
	v_add_u32_e32 v85, 0x4000, v85
	v_add_u32_e32 v227, 0x600, v29
	v_cvt_f32_i32_e32 v227, v227
	v_mul_f32_e32 v227, v93, v227
	v_mul_f32_e32 v227, 0x3fb8aa3b, v227
	v_exp_f32_e32 v226, v227
	s_waitcnt lgkmcnt(12)
	v_mfma_f32_16x16x32_f16 v[8:11], v[12:15], v[0:3], 0
	v_mfma_f32_16x16x32_f16 v[8:11], v[16:19], v[4:7], v[8:11]
	s_nop 7
	v_cndmask_b32_e64 v222, v8, v11, s[40:41]
	v_cndmask_b32_e64 v223, v9, v10, s[40:41]
	v_cndmask_b32_e64 v224, v10, v9, s[40:41]
	v_cndmask_b32_e64 v225, v11, v8, s[40:41]
	v_mul_f32_e32 v222, v222, v226
	v_mul_f32_e32 v223, v223, v226
	v_mul_f32_e32 v224, v224, v226
	v_mul_f32_e32 v225, v225, v226
	v_mul_f32_e32 v222, v80, v222
	v_mul_f32_e32 v223, v81, v223
	v_mul_f32_e32 v224, v82, v224
	v_mul_f32_e32 v225, v84, v225
	v_mul_f32_e32 v31, v222, v222
	v_fmac_f32_e32 v31, v223, v223
	v_fmac_f32_e32 v31, v224, v224
	v_fmac_f32_e32 v31, v225, v225
	v_add_f32_e32 v28, v28, v31
	s_mov_b64 exec, s[38:39]
	ds_write_b32 v78, v222
	ds_write_b32 v78, v223 offset:8
	ds_write_b32 v78, v224 offset:16
	ds_write_b32 v78, v225 offset:24
	s_mov_b64 exec, -1
	v_add_u32_e32 v78, v78, v79
	s_waitcnt vmcnt(4)
	ds_bpermute_b32 v12, v30, v244
	ds_bpermute_b32 v13, v30, v245
	ds_bpermute_b32 v14, v30, v246
	ds_bpermute_b32 v15, v30, v247
	ds_bpermute_b32 v16, v30, v248
	ds_bpermute_b32 v17, v30, v249
	ds_bpermute_b32 v18, v30, v250
	ds_bpermute_b32 v19, v30, v251
	global_load_dwordx4 v[244:247], v85, s[70:71]
	global_load_dwordx4 v[248:251], v85, s[70:71] offset:64
	v_add_u32_e32 v85, 0x4000, v85
	v_add_u32_e32 v227, 0x680, v29
	v_cvt_f32_i32_e32 v227, v227
	v_mul_f32_e32 v227, v93, v227
	v_mul_f32_e32 v227, 0x3fb8aa3b, v227
	v_exp_f32_e32 v226, v227
	s_waitcnt lgkmcnt(12)
	v_mfma_f32_16x16x32_f16 v[8:11], v[20:23], v[0:3], 0
	v_mfma_f32_16x16x32_f16 v[8:11], v[24:27], v[4:7], v[8:11]
	s_nop 7
	v_cndmask_b32_e64 v222, v8, v11, s[40:41]
	v_cndmask_b32_e64 v223, v9, v10, s[40:41]
	v_cndmask_b32_e64 v224, v10, v9, s[40:41]
	v_cndmask_b32_e64 v225, v11, v8, s[40:41]
	v_mul_f32_e32 v222, v222, v226
	v_mul_f32_e32 v223, v223, v226
	v_mul_f32_e32 v224, v224, v226
	v_mul_f32_e32 v225, v225, v226
	v_mul_f32_e32 v222, v80, v222
	v_mul_f32_e32 v223, v81, v223
	v_mul_f32_e32 v224, v82, v224
	v_mul_f32_e32 v225, v84, v225
	v_mul_f32_e32 v31, v222, v222
	v_fmac_f32_e32 v31, v223, v223
	v_fmac_f32_e32 v31, v224, v224
	v_fmac_f32_e32 v31, v225, v225
	v_add_f32_e32 v28, v28, v31
	s_mov_b64 exec, s[38:39]
	ds_write_b32 v78, v222
	ds_write_b32 v78, v223 offset:8
	ds_write_b32 v78, v224 offset:16
	ds_write_b32 v78, v225 offset:24
	s_mov_b64 exec, -1
	v_add_u32_e32 v78, v78, v79
	s_waitcnt vmcnt(4)
; __device__ __forceinline__ void phase_hyena(KP kp_, int hf){ asm volatile("" : "+s"(kp_)); const Params p=load_params(kp_);
;     ...
;       _Pragma("unroll 8") for (int i=0;i<64;++i){ int tl=wid+8*i;
;         const _Float16* ap=a3+(size_t)(tl*16+n)*64+kg*8;
;         f16x8 a0=*(const f16x8*)ap, a1=*(const f16x8*)(ap+32);
;         f32x4 dd={0.f,0.f,0.f,0.f};
;         dd=__builtin_amdgcn_mfma_f32_16x16x32_f16(a0,bw0,dd,0,0,0);
;         dd=__builtin_amdgcn_mfma_f32_16x16x32_f16(a1,bw1,dd,0,0,0);
;         if (n<4){ float d0=__expf(dsc*(float)(tl*16)); int lag0=tl*16+kg*4;
;           float v0=dd[0]*d0*pj0, v1=dd[1]*d0*pj1, v2=dd[2]*d0*pj2, v3=dd[3]*d0*pj3;
;           if (!side1){ Zf[2*(lag0)+order]=v0; Zf[2*(lag0+1)+order]=v1; Zf[2*(lag0+2)+order]=v2; Zf[2*(lag0+3)+order]=v3; ssl+=v0*v0+v1*v1+v2*v2+v3*v3; }
;           else { if (lag0>=1){ Zf[2*(16384-lag0)+order]=v0; ssl+=v0*v0; }
;             Zf[2*(16384-lag0-1)+order]=v1; Zf[2*(16384-lag0-2)+order]=v2; Zf[2*(16384-lag0-3)+order]=v3; ssl+=v1*v1+v2*v2+v3*v3; } }
;       }
	ds_bpermute_b32 v20, v30, v228
	ds_bpermute_b32 v21, v30, v229
	ds_bpermute_b32 v22, v30, v230
	ds_bpermute_b32 v23, v30, v231
	ds_bpermute_b32 v24, v30, v232
	ds_bpermute_b32 v25, v30, v233
	ds_bpermute_b32 v26, v30, v234
	ds_bpermute_b32 v27, v30, v235
	global_load_dwordx4 v[228:231], v85, s[70:71]
	global_load_dwordx4 v[232:235], v85, s[70:71] offset:64
	v_add_u32_e32 v85, 0x4000, v85
	v_add_u32_e32 v227, 0x700, v29
	v_cvt_f32_i32_e32 v227, v227
	v_mul_f32_e32 v227, v93, v227
	v_mul_f32_e32 v227, 0x3fb8aa3b, v227
	v_exp_f32_e32 v226, v227
	s_waitcnt lgkmcnt(12)
	v_mfma_f32_16x16x32_f16 v[8:11], v[12:15], v[0:3], 0
	v_mfma_f32_16x16x32_f16 v[8:11], v[16:19], v[4:7], v[8:11]
	s_nop 7
	v_cndmask_b32_e64 v222, v8, v11, s[40:41]
	v_cndmask_b32_e64 v223, v9, v10, s[40:41]
	v_cndmask_b32_e64 v224, v10, v9, s[40:41]
	v_cndmask_b32_e64 v225, v11, v8, s[40:41]
	v_mul_f32_e32 v222, v222, v226
	v_mul_f32_e32 v223, v223, v226
	v_mul_f32_e32 v224, v224, v226
	v_mul_f32_e32 v225, v225, v226
	v_mul_f32_e32 v222, v80, v222
	v_mul_f32_e32 v223, v81, v223
	v_mul_f32_e32 v224, v82, v224
	v_mul_f32_e32 v225, v84, v225
	v_mul_f32_e32 v31, v222, v222
	v_fmac_f32_e32 v31, v223, v223
	v_fmac_f32_e32 v31, v224, v224
	v_fmac_f32_e32 v31, v225, v225
	v_add_f32_e32 v28, v28, v31
	s_mov_b64 exec, s[38:39]
	ds_write_b32 v78, v222
	ds_write_b32 v78, v223 offset:8
	ds_write_b32 v78, v224 offset:16
	ds_write_b32 v78, v225 offset:24
	s_mov_b64 exec, -1
	v_add_u32_e32 v78, v78, v79
	s_waitcnt vmcnt(4)
	ds_bpermute_b32 v12, v30, v236
	ds_bpermute_b32 v13, v30, v237
	ds_bpermute_b32 v14, v30, v238
	ds_bpermute_b32 v15, v30, v239
	ds_bpermute_b32 v16, v30, v240
	ds_bpermute_b32 v17, v30, v241
	ds_bpermute_b32 v18, v30, v242
	ds_bpermute_b32 v19, v30, v243
	global_load_dwordx4 v[236:239], v85, s[70:71]
	global_load_dwordx4 v[240:243], v85, s[70:71] offset:64
	v_add_u32_e32 v85, 0x4000, v85
	v_add_u32_e32 v227, 0x780, v29
	v_cvt_f32_i32_e32 v227, v227
	v_mul_f32_e32 v227, v93, v227
	v_mul_f32_e32 v227, 0x3fb8aa3b, v227
	v_exp_f32_e32 v226, v227
	s_waitcnt lgkmcnt(12)
	v_mfma_f32_16x16x32_f16 v[8:11], v[20:23], v[0:3], 0
	v_mfma_f32_16x16x32_f16 v[8:11], v[24:27], v[4:7], v[8:11]
	s_nop 7
	v_cndmask_b32_e64 v222, v8, v11, s[40:41]
	v_cndmask_b32_e64 v223, v9, v10, s[40:41]
	v_cndmask_b32_e64 v224, v10, v9, s[40:41]
	v_cndmask_b32_e64 v225, v11, v8, s[40:41]
	v_mul_f32_e32 v222, v222, v226
	v_mul_f32_e32 v223, v223, v226
	v_mul_f32_e32 v224, v224, v226
	v_mul_f32_e32 v225, v225, v226
	v_mul_f32_e32 v222, v80, v222
	v_mul_f32_e32 v223, v81, v223
	v_mul_f32_e32 v224, v82, v224
	v_mul_f32_e32 v225, v84, v225
	v_mul_f32_e32 v31, v222, v222
	v_fmac_f32_e32 v31, v223, v223
	v_fmac_f32_e32 v31, v224, v224
	v_fmac_f32_e32 v31, v225, v225
	v_add_f32_e32 v28, v28, v31
	s_mov_b64 exec, s[38:39]
	ds_write_b32 v78, v222
	ds_write_b32 v78, v223 offset:8
	ds_write_b32 v78, v224 offset:16
	ds_write_b32 v78, v225 offset:24
	s_mov_b64 exec, -1
	v_add_u32_e32 v78, v78, v79
	s_waitcnt vmcnt(4)
	ds_bpermute_b32 v20, v30, v244
	ds_bpermute_b32 v21, v30, v245
	ds_bpermute_b32 v22, v30, v246
	ds_bpermute_b32 v23, v30, v247
	ds_bpermute_b32 v24, v30, v248
	ds_bpermute_b32 v25, v30, v249
	ds_bpermute_b32 v26, v30, v250
	ds_bpermute_b32 v27, v30, v251
	global_load_dwordx4 v[244:247], v85, s[70:71]
	global_load_dwordx4 v[248:251], v85, s[70:71] offset:64
	v_add_u32_e32 v85, 0x4000, v85
	v_add_u32_e32 v227, 0x800, v29
	v_cvt_f32_i32_e32 v227, v227
	v_mul_f32_e32 v227, v93, v227
	v_mul_f32_e32 v227, 0x3fb8aa3b, v227
	v_exp_f32_e32 v226, v227
	s_waitcnt lgkmcnt(12)
	v_mfma_f32_16x16x32_f16 v[8:11], v[12:15], v[0:3], 0
	v_mfma_f32_16x16x32_f16 v[8:11], v[16:19], v[4:7], v[8:11]
	s_nop 7
	v_cndmask_b32_e64 v222, v8, v11, s[40:41]
	v_cndmask_b32_e64 v223, v9, v10, s[40:41]
	v_cndmask_b32_e64 v224, v10, v9, s[40:41]
	v_cndmask_b32_e64 v225, v11, v8, s[40:41]
	v_mul_f32_e32 v222, v222, v226
	v_mul_f32_e32 v223, v223, v226
	v_mul_f32_e32 v224, v224, v226
	v_mul_f32_e32 v225, v225, v226
	v_mul_f32_e32 v222, v80, v222
	v_mul_f32_e32 v223, v81, v223
	v_mul_f32_e32 v224, v82, v224
	v_mul_f32_e32 v225, v84, v225
	v_mul_f32_e32 v31, v222, v222
	v_fmac_f32_e32 v31, v223, v223
	v_fmac_f32_e32 v31, v224, v224
	v_fmac_f32_e32 v31, v225, v225
	v_add_f32_e32 v28, v28, v31
	s_mov_b64 exec, s[38:39]
	ds_write_b32 v78, v222
	ds_write_b32 v78, v223 offset:8
	ds_write_b32 v78, v224 offset:16
	ds_write_b32 v78, v225 offset:24
	s_mov_b64 exec, -1
	v_add_u32_e32 v78, v78, v79
	s_waitcnt vmcnt(4)
	ds_bpermute_b32 v12, v30, v228
	ds_bpermute_b32 v13, v30, v229
	ds_bpermute_b32 v14, v30, v230
	ds_bpermute_b32 v15, v30, v231
	ds_bpermute_b32 v16, v30, v232
	ds_bpermute_b32 v17, v30, v233
	ds_bpermute_b32 v18, v30, v234
	ds_bpermute_b32 v19, v30, v235
	global_load_dwordx4 v[228:231], v85, s[70:71]
	global_load_dwordx4 v[232:235], v85, s[70:71] offset:64
	v_add_u32_e32 v85, 0x4000, v85
	v_add_u32_e32 v227, 0x880, v29
	v_cvt_f32_i32_e32 v227, v227
	v_mul_f32_e32 v227, v93, v227
	v_mul_f32_e32 v227, 0x3fb8aa3b, v227
	v_exp_f32_e32 v226, v227
	s_waitcnt lgkmcnt(12)
	v_mfma_f32_16x16x32_f16 v[8:11], v[20:23], v[0:3], 0
	v_mfma_f32_16x16x32_f16 v[8:11], v[24:27], v[4:7], v[8:11]
	s_nop 7
	v_cndmask_b32_e64 v222, v8, v11, s[40:41]
	v_cndmask_b32_e64 v223, v9, v10, s[40:41]
	v_cndmask_b32_e64 v224, v10, v9, s[40:41]
	v_cndmask_b32_e64 v225, v11, v8, s[40:41]
	v_mul_f32_e32 v222, v222, v226
	v_mul_f32_e32 v223, v223, v226
	v_mul_f32_e32 v224, v224, v226
	v_mul_f32_e32 v225, v225, v226
	v_mul_f32_e32 v222, v80, v222
	v_mul_f32_e32 v223, v81, v223
	v_mul_f32_e32 v224, v82, v224
	v_mul_f32_e32 v225, v84, v225
	v_mul_f32_e32 v31, v222, v222
	v_fmac_f32_e32 v31, v223, v223
	v_fmac_f32_e32 v31, v224, v224
	v_fmac_f32_e32 v31, v225, v225
	v_add_f32_e32 v28, v28, v31
	s_mov_b64 exec, s[38:39]
	ds_write_b32 v78, v222
	ds_write_b32 v78, v223 offset:8
	ds_write_b32 v78, v224 offset:16
	ds_write_b32 v78, v225 offset:24
	s_mov_b64 exec, -1
	v_add_u32_e32 v78, v78, v79
	s_waitcnt vmcnt(4)
; __device__ __forceinline__ void phase_hyena(KP kp_, int hf){ asm volatile("" : "+s"(kp_)); const Params p=load_params(kp_);
;     ...
;       _Pragma("unroll 8") for (int i=0;i<64;++i){ int tl=wid+8*i;
;         const _Float16* ap=a3+(size_t)(tl*16+n)*64+kg*8;
;         f16x8 a0=*(const f16x8*)ap, a1=*(const f16x8*)(ap+32);
;         f32x4 dd={0.f,0.f,0.f,0.f};
;         dd=__builtin_amdgcn_mfma_f32_16x16x32_f16(a0,bw0,dd,0,0,0);
;         dd=__builtin_amdgcn_mfma_f32_16x16x32_f16(a1,bw1,dd,0,0,0);
;         if (n<4){ float d0=__expf(dsc*(float)(tl*16)); int lag0=tl*16+kg*4;
;           float v0=dd[0]*d0*pj0, v1=dd[1]*d0*pj1, v2=dd[2]*d0*pj2, v3=dd[3]*d0*pj3;
;           if (!side1){ Zf[2*(lag0)+order]=v0; Zf[2*(lag0+1)+order]=v1; Zf[2*(lag0+2)+order]=v2; Zf[2*(lag0+3)+order]=v3; ssl+=v0*v0+v1*v1+v2*v2+v3*v3; }
;           else { if (lag0>=1){ Zf[2*(16384-lag0)+order]=v0; ssl+=v0*v0; }
;             Zf[2*(16384-lag0-1)+order]=v1; Zf[2*(16384-lag0-2)+order]=v2; Zf[2*(16384-lag0-3)+order]=v3; ssl+=v1*v1+v2*v2+v3*v3; } }
;       }
	ds_bpermute_b32 v20, v30, v236
	ds_bpermute_b32 v21, v30, v237
	ds_bpermute_b32 v22, v30, v238
	ds_bpermute_b32 v23, v30, v239
	ds_bpermute_b32 v24, v30, v240
	ds_bpermute_b32 v25, v30, v241
	ds_bpermute_b32 v26, v30, v242
	ds_bpermute_b32 v27, v30, v243
	global_load_dwordx4 v[236:239], v85, s[70:71]
	global_load_dwordx4 v[240:243], v85, s[70:71] offset:64
	v_add_u32_e32 v85, 0x4000, v85
	v_add_u32_e32 v227, 0x900, v29
	v_cvt_f32_i32_e32 v227, v227
	v_mul_f32_e32 v227, v93, v227
	v_mul_f32_e32 v227, 0x3fb8aa3b, v227
	v_exp_f32_e32 v226, v227
	s_waitcnt lgkmcnt(12)
	v_mfma_f32_16x16x32_f16 v[8:11], v[12:15], v[0:3], 0
	v_mfma_f32_16x16x32_f16 v[8:11], v[16:19], v[4:7], v[8:11]
	s_nop 7
	v_cndmask_b32_e64 v222, v8, v11, s[40:41]
	v_cndmask_b32_e64 v223, v9, v10, s[40:41]
	v_cndmask_b32_e64 v224, v10, v9, s[40:41]
	v_cndmask_b32_e64 v225, v11, v8, s[40:41]
	v_mul_f32_e32 v222, v222, v226
	v_mul_f32_e32 v223, v223, v226
	v_mul_f32_e32 v224, v224, v226
	v_mul_f32_e32 v225, v225, v226
	v_mul_f32_e32 v222, v80, v222
	v_mul_f32_e32 v223, v81, v223
	v_mul_f32_e32 v224, v82, v224
	v_mul_f32_e32 v225, v84, v225
	v_mul_f32_e32 v31, v222, v222
	v_fmac_f32_e32 v31, v223, v223
	v_fmac_f32_e32 v31, v224, v224
	v_fmac_f32_e32 v31, v225, v225
	v_add_f32_e32 v28, v28, v31
	s_mov_b64 exec, s[38:39]
	ds_write_b32 v78, v222
	ds_write_b32 v78, v223 offset:8
	ds_write_b32 v78, v224 offset:16
	ds_write_b32 v78, v225 offset:24
	s_mov_b64 exec, -1
	v_add_u32_e32 v78, v78, v79
	s_waitcnt vmcnt(4)
	ds_bpermute_b32 v12, v30, v244
	ds_bpermute_b32 v13, v30, v245
	ds_bpermute_b32 v14, v30, v246
	ds_bpermute_b32 v15, v30, v247
	ds_bpermute_b32 v16, v30, v248
	ds_bpermute_b32 v17, v30, v249
	ds_bpermute_b32 v18, v30, v250
	ds_bpermute_b32 v19, v30, v251
	global_load_dwordx4 v[244:247], v85, s[70:71]
	global_load_dwordx4 v[248:251], v85, s[70:71] offset:64
	v_add_u32_e32 v85, 0x4000, v85
	v_add_u32_e32 v227, 0x980, v29
	v_cvt_f32_i32_e32 v227, v227
	v_mul_f32_e32 v227, v93, v227
	v_mul_f32_e32 v227, 0x3fb8aa3b, v227
	v_exp_f32_e32 v226, v227
	s_waitcnt lgkmcnt(12)
	v_mfma_f32_16x16x32_f16 v[8:11], v[20:23], v[0:3], 0
	v_mfma_f32_16x16x32_f16 v[8:11], v[24:27], v[4:7], v[8:11]
	s_nop 7
	v_cndmask_b32_e64 v222, v8, v11, s[40:41]
	v_cndmask_b32_e64 v223, v9, v10, s[40:41]
	v_cndmask_b32_e64 v224, v10, v9, s[40:41]
	v_cndmask_b32_e64 v225, v11, v8, s[40:41]
	v_mul_f32_e32 v222, v222, v226
	v_mul_f32_e32 v223, v223, v226
	v_mul_f32_e32 v224, v224, v226
	v_mul_f32_e32 v225, v225, v226
	v_mul_f32_e32 v222, v80, v222
	v_mul_f32_e32 v223, v81, v223
	v_mul_f32_e32 v224, v82, v224
	v_mul_f32_e32 v225, v84, v225
	v_mul_f32_e32 v31, v222, v222
	v_fmac_f32_e32 v31, v223, v223
	v_fmac_f32_e32 v31, v224, v224
	v_fmac_f32_e32 v31, v225, v225
	v_add_f32_e32 v28, v28, v31
	s_mov_b64 exec, s[38:39]
	ds_write_b32 v78, v222
	ds_write_b32 v78, v223 offset:8
	ds_write_b32 v78, v224 offset:16
	ds_write_b32 v78, v225 offset:24
	s_mov_b64 exec, -1
	v_add_u32_e32 v78, v78, v79
	s_waitcnt vmcnt(4)
	ds_bpermute_b32 v20, v30, v228
	ds_bpermute_b32 v21, v30, v229
	ds_bpermute_b32 v22, v30, v230
	ds_bpermute_b32 v23, v30, v231
	ds_bpermute_b32 v24, v30, v232
	ds_bpermute_b32 v25, v30, v233
	ds_bpermute_b32 v26, v30, v234
	ds_bpermute_b32 v27, v30, v235
	global_load_dwordx4 v[228:231], v85, s[70:71]
	global_load_dwordx4 v[232:235], v85, s[70:71] offset:64
	v_add_u32_e32 v85, 0x4000, v85
	v_add_u32_e32 v227, 0xa00, v29
	v_cvt_f32_i32_e32 v227, v227
	v_mul_f32_e32 v227, v93, v227
	v_mul_f32_e32 v227, 0x3fb8aa3b, v227
	v_exp_f32_e32 v226, v227
	s_waitcnt lgkmcnt(12)
	v_mfma_f32_16x16x32_f16 v[8:11], v[12:15], v[0:3], 0
	v_mfma_f32_16x16x32_f16 v[8:11], v[16:19], v[4:7], v[8:11]
	s_nop 7
	v_cndmask_b32_e64 v222, v8, v11, s[40:41]
	v_cndmask_b32_e64 v223, v9, v10, s[40:41]
	v_cndmask_b32_e64 v224, v10, v9, s[40:41]
	v_cndmask_b32_e64 v225, v11, v8, s[40:41]
	v_mul_f32_e32 v222, v222, v226
	v_mul_f32_e32 v223, v223, v226
	v_mul_f32_e32 v224, v224, v226
	v_mul_f32_e32 v225, v225, v226
	v_mul_f32_e32 v222, v80, v222
	v_mul_f32_e32 v223, v81, v223
	v_mul_f32_e32 v224, v82, v224
	v_mul_f32_e32 v225, v84, v225
	v_mul_f32_e32 v31, v222, v222
	v_fmac_f32_e32 v31, v223, v223
	v_fmac_f32_e32 v31, v224, v224
	v_fmac_f32_e32 v31, v225, v225
	v_add_f32_e32 v28, v28, v31
	s_mov_b64 exec, s[38:39]
	ds_write_b32 v78, v222
	ds_write_b32 v78, v223 offset:8
	ds_write_b32 v78, v224 offset:16
	ds_write_b32 v78, v225 offset:24
	s_mov_b64 exec, -1
	v_add_u32_e32 v78, v78, v79
	s_waitcnt vmcnt(4)
	ds_bpermute_b32 v12, v30, v236
	ds_bpermute_b32 v13, v30, v237
	ds_bpermute_b32 v14, v30, v238
	ds_bpermute_b32 v15, v30, v239
	ds_bpermute_b32 v16, v30, v240
	ds_bpermute_b32 v17, v30, v241
	ds_bpermute_b32 v18, v30, v242
	ds_bpermute_b32 v19, v30, v243
	global_load_dwordx4 v[236:239], v85, s[70:71]
	global_load_dwordx4 v[240:243], v85, s[70:71] offset:64
	v_add_u32_e32 v85, 0x4000, v85
	v_add_u32_e32 v227, 0xa80, v29
	v_cvt_f32_i32_e32 v227, v227
	v_mul_f32_e32 v227, v93, v227
	v_mul_f32_e32 v227, 0x3fb8aa3b, v227
	v_exp_f32_e32 v226, v227
	s_waitcnt lgkmcnt(12)
	v_mfma_f32_16x16x32_f16 v[8:11], v[20:23], v[0:3], 0
	v_mfma_f32_16x16x32_f16 v[8:11], v[24:27], v[4:7], v[8:11]
	s_nop 7
	v_cndmask_b32_e64 v222, v8, v11, s[40:41]
	v_cndmask_b32_e64 v223, v9, v10, s[40:41]
	v_cndmask_b32_e64 v224, v10, v9, s[40:41]
	v_cndmask_b32_e64 v225, v11, v8, s[40:41]
	v_mul_f32_e32 v222, v222, v226
	v_mul_f32_e32 v223, v223, v226
	v_mul_f32_e32 v224, v224, v226
	v_mul_f32_e32 v225, v225, v226
	v_mul_f32_e32 v222, v80, v222
	v_mul_f32_e32 v223, v81, v223
	v_mul_f32_e32 v224, v82, v224
	v_mul_f32_e32 v225, v84, v225
	v_mul_f32_e32 v31, v222, v222
	v_fmac_f32_e32 v31, v223, v223
	v_fmac_f32_e32 v31, v224, v224
	v_fmac_f32_e32 v31, v225, v225
	v_add_f32_e32 v28, v28, v31
	s_mov_b64 exec, s[38:39]
	ds_write_b32 v78, v222
	ds_write_b32 v78, v223 offset:8
	ds_write_b32 v78, v224 offset:16
	ds_write_b32 v78, v225 offset:24
	s_mov_b64 exec, -1
	v_add_u32_e32 v78, v78, v79
	s_waitcnt vmcnt(4)
; __device__ __forceinline__ void phase_hyena(KP kp_, int hf){ asm volatile("" : "+s"(kp_)); const Params p=load_params(kp_);
;     ...
;       _Pragma("unroll 8") for (int i=0;i<64;++i){ int tl=wid+8*i;
;         const _Float16* ap=a3+(size_t)(tl*16+n)*64+kg*8;
;         f16x8 a0=*(const f16x8*)ap, a1=*(const f16x8*)(ap+32);
;         f32x4 dd={0.f,0.f,0.f,0.f};
;         dd=__builtin_amdgcn_mfma_f32_16x16x32_f16(a0,bw0,dd,0,0,0);
;         dd=__builtin_amdgcn_mfma_f32_16x16x32_f16(a1,bw1,dd,0,0,0);
;         if (n<4){ float d0=__expf(dsc*(float)(tl*16)); int lag0=tl*16+kg*4;
;           float v0=dd[0]*d0*pj0, v1=dd[1]*d0*pj1, v2=dd[2]*d0*pj2, v3=dd[3]*d0*pj3;
;           if (!side1){ Zf[2*(lag0)+order]=v0; Zf[2*(lag0+1)+order]=v1; Zf[2*(lag0+2)+order]=v2; Zf[2*(lag0+3)+order]=v3; ssl+=v0*v0+v1*v1+v2*v2+v3*v3; }
;           else { if (lag0>=1){ Zf[2*(16384-lag0)+order]=v0; ssl+=v0*v0; }
;             Zf[2*(16384-lag0-1)+order]=v1; Zf[2*(16384-lag0-2)+order]=v2; Zf[2*(16384-lag0-3)+order]=v3; ssl+=v1*v1+v2*v2+v3*v3; } }
;       }
	ds_bpermute_b32 v20, v30, v244
	ds_bpermute_b32 v21, v30, v245
	ds_bpermute_b32 v22, v30, v246
	ds_bpermute_b32 v23, v30, v247
	ds_bpermute_b32 v24, v30, v248
	ds_bpermute_b32 v25, v30, v249
	ds_bpermute_b32 v26, v30, v250
	ds_bpermute_b32 v27, v30, v251
	global_load_dwordx4 v[244:247], v85, s[70:71]
	global_load_dwordx4 v[248:251], v85, s[70:71] offset:64
	v_add_u32_e32 v85, 0x4000, v85
	v_add_u32_e32 v227, 0xb00, v29
	v_cvt_f32_i32_e32 v227, v227
	v_mul_f32_e32 v227, v93, v227
	v_mul_f32_e32 v227, 0x3fb8aa3b, v227
	v_exp_f32_e32 v226, v227
	s_waitcnt lgkmcnt(12)
	v_mfma_f32_16x16x32_f16 v[8:11], v[12:15], v[0:3], 0
	v_mfma_f32_16x16x32_f16 v[8:11], v[16:19], v[4:7], v[8:11]
	s_nop 7
	v_cndmask_b32_e64 v222, v8, v11, s[40:41]
	v_cndmask_b32_e64 v223, v9, v10, s[40:41]
	v_cndmask_b32_e64 v224, v10, v9, s[40:41]
	v_cndmask_b32_e64 v225, v11, v8, s[40:41]
	v_mul_f32_e32 v222, v222, v226
	v_mul_f32_e32 v223, v223, v226
	v_mul_f32_e32 v224, v224, v226
	v_mul_f32_e32 v225, v225, v226
	v_mul_f32_e32 v222, v80, v222
	v_mul_f32_e32 v223, v81, v223
	v_mul_f32_e32 v224, v82, v224
	v_mul_f32_e32 v225, v84, v225
	v_mul_f32_e32 v31, v222, v222
	v_fmac_f32_e32 v31, v223, v223
	v_fmac_f32_e32 v31, v224, v224
	v_fmac_f32_e32 v31, v225, v225
	v_add_f32_e32 v28, v28, v31
	s_mov_b64 exec, s[38:39]
	ds_write_b32 v78, v222
	ds_write_b32 v78, v223 offset:8
	ds_write_b32 v78, v224 offset:16
	ds_write_b32 v78, v225 offset:24
	s_mov_b64 exec, -1
	v_add_u32_e32 v78, v78, v79
	s_waitcnt vmcnt(4)
	ds_bpermute_b32 v12, v30, v228
	ds_bpermute_b32 v13, v30, v229
	ds_bpermute_b32 v14, v30, v230
	ds_bpermute_b32 v15, v30, v231
	ds_bpermute_b32 v16, v30, v232
	ds_bpermute_b32 v17, v30, v233
	ds_bpermute_b32 v18, v30, v234
	ds_bpermute_b32 v19, v30, v235
	global_load_dwordx4 v[228:231], v85, s[70:71]
	global_load_dwordx4 v[232:235], v85, s[70:71] offset:64
	v_add_u32_e32 v85, 0x4000, v85
	v_add_u32_e32 v227, 0xb80, v29
	v_cvt_f32_i32_e32 v227, v227
	v_mul_f32_e32 v227, v93, v227
	v_mul_f32_e32 v227, 0x3fb8aa3b, v227
	v_exp_f32_e32 v226, v227
	s_waitcnt lgkmcnt(12)
	v_mfma_f32_16x16x32_f16 v[8:11], v[20:23], v[0:3], 0
	v_mfma_f32_16x16x32_f16 v[8:11], v[24:27], v[4:7], v[8:11]
	s_nop 7
	v_cndmask_b32_e64 v222, v8, v11, s[40:41]
	v_cndmask_b32_e64 v223, v9, v10, s[40:41]
	v_cndmask_b32_e64 v224, v10, v9, s[40:41]
	v_cndmask_b32_e64 v225, v11, v8, s[40:41]
	v_mul_f32_e32 v222, v222, v226
	v_mul_f32_e32 v223, v223, v226
	v_mul_f32_e32 v224, v224, v226
	v_mul_f32_e32 v225, v225, v226
	v_mul_f32_e32 v222, v80, v222
	v_mul_f32_e32 v223, v81, v223
	v_mul_f32_e32 v224, v82, v224
	v_mul_f32_e32 v225, v84, v225
	v_mul_f32_e32 v31, v222, v222
	v_fmac_f32_e32 v31, v223, v223
	v_fmac_f32_e32 v31, v224, v224
	v_fmac_f32_e32 v31, v225, v225
	v_add_f32_e32 v28, v28, v31
	s_mov_b64 exec, s[38:39]
	ds_write_b32 v78, v222
	ds_write_b32 v78, v223 offset:8
	ds_write_b32 v78, v224 offset:16
	ds_write_b32 v78, v225 offset:24
	s_mov_b64 exec, -1
	v_add_u32_e32 v78, v78, v79
	s_waitcnt vmcnt(4)
	ds_bpermute_b32 v20, v30, v236
	ds_bpermute_b32 v21, v30, v237
	ds_bpermute_b32 v22, v30, v238
	ds_bpermute_b32 v23, v30, v239
	ds_bpermute_b32 v24, v30, v240
	ds_bpermute_b32 v25, v30, v241
	ds_bpermute_b32 v26, v30, v242
	ds_bpermute_b32 v27, v30, v243
	global_load_dwordx4 v[236:239], v85, s[70:71]
	global_load_dwordx4 v[240:243], v85, s[70:71] offset:64
	v_add_u32_e32 v85, 0x4000, v85
	v_add_u32_e32 v227, 0xc00, v29
	v_cvt_f32_i32_e32 v227, v227
	v_mul_f32_e32 v227, v93, v227
	v_mul_f32_e32 v227, 0x3fb8aa3b, v227
	v_exp_f32_e32 v226, v227
	s_waitcnt lgkmcnt(12)
	v_mfma_f32_16x16x32_f16 v[8:11], v[12:15], v[0:3], 0
	v_mfma_f32_16x16x32_f16 v[8:11], v[16:19], v[4:7], v[8:11]
	s_nop 7
	v_cndmask_b32_e64 v222, v8, v11, s[40:41]
	v_cndmask_b32_e64 v223, v9, v10, s[40:41]
	v_cndmask_b32_e64 v224, v10, v9, s[40:41]
	v_cndmask_b32_e64 v225, v11, v8, s[40:41]
	v_mul_f32_e32 v222, v222, v226
	v_mul_f32_e32 v223, v223, v226
	v_mul_f32_e32 v224, v224, v226
	v_mul_f32_e32 v225, v225, v226
	v_mul_f32_e32 v222, v80, v222
	v_mul_f32_e32 v223, v81, v223
	v_mul_f32_e32 v224, v82, v224
	v_mul_f32_e32 v225, v84, v225
	v_mul_f32_e32 v31, v222, v222
	v_fmac_f32_e32 v31, v223, v223
	v_fmac_f32_e32 v31, v224, v224
	v_fmac_f32_e32 v31, v225, v225
	v_add_f32_e32 v28, v28, v31
	s_mov_b64 exec, s[38:39]
	ds_write_b32 v78, v222
	ds_write_b32 v78, v223 offset:8
	ds_write_b32 v78, v224 offset:16
	ds_write_b32 v78, v225 offset:24
	s_mov_b64 exec, -1
	v_add_u32_e32 v78, v78, v79
	s_waitcnt vmcnt(4)
	ds_bpermute_b32 v12, v30, v244
	ds_bpermute_b32 v13, v30, v245
	ds_bpermute_b32 v14, v30, v246
	ds_bpermute_b32 v15, v30, v247
	ds_bpermute_b32 v16, v30, v248
	ds_bpermute_b32 v17, v30, v249
	ds_bpermute_b32 v18, v30, v250
	ds_bpermute_b32 v19, v30, v251
	global_load_dwordx4 v[244:247], v85, s[70:71]
	global_load_dwordx4 v[248:251], v85, s[70:71] offset:64
	v_add_u32_e32 v85, 0x4000, v85
	v_add_u32_e32 v227, 0xc80, v29
	v_cvt_f32_i32_e32 v227, v227
	v_mul_f32_e32 v227, v93, v227
	v_mul_f32_e32 v227, 0x3fb8aa3b, v227
	v_exp_f32_e32 v226, v227
	s_waitcnt lgkmcnt(12)
	v_mfma_f32_16x16x32_f16 v[8:11], v[20:23], v[0:3], 0
	v_mfma_f32_16x16x32_f16 v[8:11], v[24:27], v[4:7], v[8:11]
	s_nop 7
	v_cndmask_b32_e64 v222, v8, v11, s[40:41]
	v_cndmask_b32_e64 v223, v9, v10, s[40:41]
	v_cndmask_b32_e64 v224, v10, v9, s[40:41]
	v_cndmask_b32_e64 v225, v11, v8, s[40:41]
	v_mul_f32_e32 v222, v222, v226
	v_mul_f32_e32 v223, v223, v226
	v_mul_f32_e32 v224, v224, v226
	v_mul_f32_e32 v225, v225, v226
	v_mul_f32_e32 v222, v80, v222
	v_mul_f32_e32 v223, v81, v223
	v_mul_f32_e32 v224, v82, v224
	v_mul_f32_e32 v225, v84, v225
	v_mul_f32_e32 v31, v222, v222
	v_fmac_f32_e32 v31, v223, v223
	v_fmac_f32_e32 v31, v224, v224
	v_fmac_f32_e32 v31, v225, v225
	v_add_f32_e32 v28, v28, v31
	s_mov_b64 exec, s[38:39]
	ds_write_b32 v78, v222
	ds_write_b32 v78, v223 offset:8
	ds_write_b32 v78, v224 offset:16
	ds_write_b32 v78, v225 offset:24
	s_mov_b64 exec, -1
	v_add_u32_e32 v78, v78, v79
	s_waitcnt vmcnt(4)
; __device__ __forceinline__ void phase_hyena(KP kp_, int hf){ asm volatile("" : "+s"(kp_)); const Params p=load_params(kp_);
;     ...
;       _Pragma("unroll 8") for (int i=0;i<64;++i){ int tl=wid+8*i;
;         const _Float16* ap=a3+(size_t)(tl*16+n)*64+kg*8;
;         f16x8 a0=*(const f16x8*)ap, a1=*(const f16x8*)(ap+32);
;         f32x4 dd={0.f,0.f,0.f,0.f};
;         dd=__builtin_amdgcn_mfma_f32_16x16x32_f16(a0,bw0,dd,0,0,0);
;         dd=__builtin_amdgcn_mfma_f32_16x16x32_f16(a1,bw1,dd,0,0,0);
;         if (n<4){ float d0=__expf(dsc*(float)(tl*16)); int lag0=tl*16+kg*4;
;           float v0=dd[0]*d0*pj0, v1=dd[1]*d0*pj1, v2=dd[2]*d0*pj2, v3=dd[3]*d0*pj3;
;           if (!side1){ Zf[2*(lag0)+order]=v0; Zf[2*(lag0+1)+order]=v1; Zf[2*(lag0+2)+order]=v2; Zf[2*(lag0+3)+order]=v3; ssl+=v0*v0+v1*v1+v2*v2+v3*v3; }
;           else { if (lag0>=1){ Zf[2*(16384-lag0)+order]=v0; ssl+=v0*v0; }
;             Zf[2*(16384-lag0-1)+order]=v1; Zf[2*(16384-lag0-2)+order]=v2; Zf[2*(16384-lag0-3)+order]=v3; ssl+=v1*v1+v2*v2+v3*v3; } }
;       }
	ds_bpermute_b32 v20, v30, v228
	ds_bpermute_b32 v21, v30, v229
	ds_bpermute_b32 v22, v30, v230
	ds_bpermute_b32 v23, v30, v231
	ds_bpermute_b32 v24, v30, v232
	ds_bpermute_b32 v25, v30, v233
	ds_bpermute_b32 v26, v30, v234
	ds_bpermute_b32 v27, v30, v235
	global_load_dwordx4 v[228:231], v85, s[70:71]
	global_load_dwordx4 v[232:235], v85, s[70:71] offset:64
	v_add_u32_e32 v85, 0x4000, v85
	v_add_u32_e32 v227, 0xd00, v29
	v_cvt_f32_i32_e32 v227, v227
	v_mul_f32_e32 v227, v93, v227
	v_mul_f32_e32 v227, 0x3fb8aa3b, v227
	v_exp_f32_e32 v226, v227
	s_waitcnt lgkmcnt(12)
	v_mfma_f32_16x16x32_f16 v[8:11], v[12:15], v[0:3], 0
	v_mfma_f32_16x16x32_f16 v[8:11], v[16:19], v[4:7], v[8:11]
	s_nop 7
	v_cndmask_b32_e64 v222, v8, v11, s[40:41]
	v_cndmask_b32_e64 v223, v9, v10, s[40:41]
	v_cndmask_b32_e64 v224, v10, v9, s[40:41]
	v_cndmask_b32_e64 v225, v11, v8, s[40:41]
	v_mul_f32_e32 v222, v222, v226
	v_mul_f32_e32 v223, v223, v226
	v_mul_f32_e32 v224, v224, v226
	v_mul_f32_e32 v225, v225, v226
	v_mul_f32_e32 v222, v80, v222
	v_mul_f32_e32 v223, v81, v223
	v_mul_f32_e32 v224, v82, v224
	v_mul_f32_e32 v225, v84, v225
	v_mul_f32_e32 v31, v222, v222
	v_fmac_f32_e32 v31, v223, v223
	v_fmac_f32_e32 v31, v224, v224
	v_fmac_f32_e32 v31, v225, v225
	v_add_f32_e32 v28, v28, v31
	s_mov_b64 exec, s[38:39]
	ds_write_b32 v78, v222
	ds_write_b32 v78, v223 offset:8
	ds_write_b32 v78, v224 offset:16
	ds_write_b32 v78, v225 offset:24
	s_mov_b64 exec, -1
	v_add_u32_e32 v78, v78, v79
	s_waitcnt vmcnt(4)
	ds_bpermute_b32 v12, v30, v236
	ds_bpermute_b32 v13, v30, v237
	ds_bpermute_b32 v14, v30, v238
	ds_bpermute_b32 v15, v30, v239
	ds_bpermute_b32 v16, v30, v240
	ds_bpermute_b32 v17, v30, v241
	ds_bpermute_b32 v18, v30, v242
	ds_bpermute_b32 v19, v30, v243
	global_load_dwordx4 v[236:239], v85, s[70:71]
	global_load_dwordx4 v[240:243], v85, s[70:71] offset:64
	v_add_u32_e32 v85, 0x4000, v85
	v_add_u32_e32 v227, 0xd80, v29
	v_cvt_f32_i32_e32 v227, v227
	v_mul_f32_e32 v227, v93, v227
	v_mul_f32_e32 v227, 0x3fb8aa3b, v227
	v_exp_f32_e32 v226, v227
	s_waitcnt lgkmcnt(12)
	v_mfma_f32_16x16x32_f16 v[8:11], v[20:23], v[0:3], 0
	v_mfma_f32_16x16x32_f16 v[8:11], v[24:27], v[4:7], v[8:11]
	s_nop 7
	v_cndmask_b32_e64 v222, v8, v11, s[40:41]
	v_cndmask_b32_e64 v223, v9, v10, s[40:41]
	v_cndmask_b32_e64 v224, v10, v9, s[40:41]
	v_cndmask_b32_e64 v225, v11, v8, s[40:41]
	v_mul_f32_e32 v222, v222, v226
	v_mul_f32_e32 v223, v223, v226
	v_mul_f32_e32 v224, v224, v226
	v_mul_f32_e32 v225, v225, v226
	v_mul_f32_e32 v222, v80, v222
	v_mul_f32_e32 v223, v81, v223
	v_mul_f32_e32 v224, v82, v224
	v_mul_f32_e32 v225, v84, v225
	v_mul_f32_e32 v31, v222, v222
	v_fmac_f32_e32 v31, v223, v223
	v_fmac_f32_e32 v31, v224, v224
	v_fmac_f32_e32 v31, v225, v225
	v_add_f32_e32 v28, v28, v31
	s_mov_b64 exec, s[38:39]
	ds_write_b32 v78, v222
	ds_write_b32 v78, v223 offset:8
	ds_write_b32 v78, v224 offset:16
	ds_write_b32 v78, v225 offset:24
	s_mov_b64 exec, -1
	v_add_u32_e32 v78, v78, v79
	s_waitcnt vmcnt(4)
	ds_bpermute_b32 v20, v30, v244
	ds_bpermute_b32 v21, v30, v245
	ds_bpermute_b32 v22, v30, v246
	ds_bpermute_b32 v23, v30, v247
	ds_bpermute_b32 v24, v30, v248
	ds_bpermute_b32 v25, v30, v249
	ds_bpermute_b32 v26, v30, v250
	ds_bpermute_b32 v27, v30, v251
	global_load_dwordx4 v[244:247], v85, s[70:71]
	global_load_dwordx4 v[248:251], v85, s[70:71] offset:64
	v_add_u32_e32 v85, 0x4000, v85
	v_add_u32_e32 v227, 0xe00, v29
	v_cvt_f32_i32_e32 v227, v227
	v_mul_f32_e32 v227, v93, v227
	v_mul_f32_e32 v227, 0x3fb8aa3b, v227
	v_exp_f32_e32 v226, v227
	s_waitcnt lgkmcnt(12)
	v_mfma_f32_16x16x32_f16 v[8:11], v[12:15], v[0:3], 0
	v_mfma_f32_16x16x32_f16 v[8:11], v[16:19], v[4:7], v[8:11]
	s_nop 7
	v_cndmask_b32_e64 v222, v8, v11, s[40:41]
	v_cndmask_b32_e64 v223, v9, v10, s[40:41]
	v_cndmask_b32_e64 v224, v10, v9, s[40:41]
	v_cndmask_b32_e64 v225, v11, v8, s[40:41]
	v_mul_f32_e32 v222, v222, v226
	v_mul_f32_e32 v223, v223, v226
	v_mul_f32_e32 v224, v224, v226
	v_mul_f32_e32 v225, v225, v226
	v_mul_f32_e32 v222, v80, v222
	v_mul_f32_e32 v223, v81, v223
	v_mul_f32_e32 v224, v82, v224
	v_mul_f32_e32 v225, v84, v225
	v_mul_f32_e32 v31, v222, v222
	v_fmac_f32_e32 v31, v223, v223
	v_fmac_f32_e32 v31, v224, v224
	v_fmac_f32_e32 v31, v225, v225
	v_add_f32_e32 v28, v28, v31
	s_mov_b64 exec, s[38:39]
	ds_write_b32 v78, v222
	ds_write_b32 v78, v223 offset:8
	ds_write_b32 v78, v224 offset:16
	ds_write_b32 v78, v225 offset:24
	s_mov_b64 exec, -1
	v_add_u32_e32 v78, v78, v79
	s_waitcnt vmcnt(4)
	ds_bpermute_b32 v12, v30, v228
	ds_bpermute_b32 v13, v30, v229
	ds_bpermute_b32 v14, v30, v230
	ds_bpermute_b32 v15, v30, v231
	ds_bpermute_b32 v16, v30, v232
	ds_bpermute_b32 v17, v30, v233
	ds_bpermute_b32 v18, v30, v234
	ds_bpermute_b32 v19, v30, v235
	global_load_dwordx4 v[228:231], v85, s[70:71]
	global_load_dwordx4 v[232:235], v85, s[70:71] offset:64
	v_add_u32_e32 v85, 0x4000, v85
	v_add_u32_e32 v227, 0xe80, v29
	v_cvt_f32_i32_e32 v227, v227
	v_mul_f32_e32 v227, v93, v227
	v_mul_f32_e32 v227, 0x3fb8aa3b, v227
	v_exp_f32_e32 v226, v227
	s_waitcnt lgkmcnt(12)
	v_mfma_f32_16x16x32_f16 v[8:11], v[20:23], v[0:3], 0
	v_mfma_f32_16x16x32_f16 v[8:11], v[24:27], v[4:7], v[8:11]
	s_nop 7
	v_cndmask_b32_e64 v222, v8, v11, s[40:41]
	v_cndmask_b32_e64 v223, v9, v10, s[40:41]
	v_cndmask_b32_e64 v224, v10, v9, s[40:41]
	v_cndmask_b32_e64 v225, v11, v8, s[40:41]
	v_mul_f32_e32 v222, v222, v226
	v_mul_f32_e32 v223, v223, v226
	v_mul_f32_e32 v224, v224, v226
	v_mul_f32_e32 v225, v225, v226
	v_mul_f32_e32 v222, v80, v222
	v_mul_f32_e32 v223, v81, v223
	v_mul_f32_e32 v224, v82, v224
	v_mul_f32_e32 v225, v84, v225
	v_mul_f32_e32 v31, v222, v222
	v_fmac_f32_e32 v31, v223, v223
	v_fmac_f32_e32 v31, v224, v224
	v_fmac_f32_e32 v31, v225, v225
	v_add_f32_e32 v28, v28, v31
	s_mov_b64 exec, s[38:39]
	ds_write_b32 v78, v222
	ds_write_b32 v78, v223 offset:8
	ds_write_b32 v78, v224 offset:16
	ds_write_b32 v78, v225 offset:24
	s_mov_b64 exec, -1
	v_add_u32_e32 v78, v78, v79
	s_waitcnt vmcnt(4)
; __device__ __forceinline__ void phase_hyena(KP kp_, int hf){ asm volatile("" : "+s"(kp_)); const Params p=load_params(kp_);
;     ...
;       _Pragma("unroll 8") for (int i=0;i<64;++i){ int tl=wid+8*i;
;         const _Float16* ap=a3+(size_t)(tl*16+n)*64+kg*8;
;         f16x8 a0=*(const f16x8*)ap, a1=*(const f16x8*)(ap+32);
;         f32x4 dd={0.f,0.f,0.f,0.f};
;         dd=__builtin_amdgcn_mfma_f32_16x16x32_f16(a0,bw0,dd,0,0,0);
;         dd=__builtin_amdgcn_mfma_f32_16x16x32_f16(a1,bw1,dd,0,0,0);
;         if (n<4){ float d0=__expf(dsc*(float)(tl*16)); int lag0=tl*16+kg*4;
;           float v0=dd[0]*d0*pj0, v1=dd[1]*d0*pj1, v2=dd[2]*d0*pj2, v3=dd[3]*d0*pj3;
;           if (!side1){ Zf[2*(lag0)+order]=v0; Zf[2*(lag0+1)+order]=v1; Zf[2*(lag0+2)+order]=v2; Zf[2*(lag0+3)+order]=v3; ssl+=v0*v0+v1*v1+v2*v2+v3*v3; }
;           else { if (lag0>=1){ Zf[2*(16384-lag0)+order]=v0; ssl+=v0*v0; }
;             Zf[2*(16384-lag0-1)+order]=v1; Zf[2*(16384-lag0-2)+order]=v2; Zf[2*(16384-lag0-3)+order]=v3; ssl+=v1*v1+v2*v2+v3*v3; } }
;       }
	ds_bpermute_b32 v20, v30, v236
	ds_bpermute_b32 v21, v30, v237
	ds_bpermute_b32 v22, v30, v238
	ds_bpermute_b32 v23, v30, v239
	ds_bpermute_b32 v24, v30, v240
	ds_bpermute_b32 v25, v30, v241
	ds_bpermute_b32 v26, v30, v242
	ds_bpermute_b32 v27, v30, v243
	global_load_dwordx4 v[236:239], v85, s[70:71]
	global_load_dwordx4 v[240:243], v85, s[70:71] offset:64
	v_add_u32_e32 v85, 0x4000, v85
	v_add_u32_e32 v227, 0xf00, v29
	v_cvt_f32_i32_e32 v227, v227
	v_mul_f32_e32 v227, v93, v227
	v_mul_f32_e32 v227, 0x3fb8aa3b, v227
	v_exp_f32_e32 v226, v227
	s_waitcnt lgkmcnt(12)
	v_mfma_f32_16x16x32_f16 v[8:11], v[12:15], v[0:3], 0
	v_mfma_f32_16x16x32_f16 v[8:11], v[16:19], v[4:7], v[8:11]
	s_nop 7
	v_cndmask_b32_e64 v222, v8, v11, s[40:41]
	v_cndmask_b32_e64 v223, v9, v10, s[40:41]
	v_cndmask_b32_e64 v224, v10, v9, s[40:41]
	v_cndmask_b32_e64 v225, v11, v8, s[40:41]
	v_mul_f32_e32 v222, v222, v226
	v_mul_f32_e32 v223, v223, v226
	v_mul_f32_e32 v224, v224, v226
	v_mul_f32_e32 v225, v225, v226
	v_mul_f32_e32 v222, v80, v222
	v_mul_f32_e32 v223, v81, v223
	v_mul_f32_e32 v224, v82, v224
	v_mul_f32_e32 v225, v84, v225
	v_mul_f32_e32 v31, v222, v222
	v_fmac_f32_e32 v31, v223, v223
	v_fmac_f32_e32 v31, v224, v224
	v_fmac_f32_e32 v31, v225, v225
	v_add_f32_e32 v28, v28, v31
	s_mov_b64 exec, s[38:39]
	ds_write_b32 v78, v222
	ds_write_b32 v78, v223 offset:8
	ds_write_b32 v78, v224 offset:16
	ds_write_b32 v78, v225 offset:24
	s_mov_b64 exec, -1
	v_add_u32_e32 v78, v78, v79
	s_waitcnt vmcnt(4)
	ds_bpermute_b32 v12, v30, v244
	ds_bpermute_b32 v13, v30, v245
	ds_bpermute_b32 v14, v30, v246
	ds_bpermute_b32 v15, v30, v247
	ds_bpermute_b32 v16, v30, v248
	ds_bpermute_b32 v17, v30, v249
	ds_bpermute_b32 v18, v30, v250
	ds_bpermute_b32 v19, v30, v251
	global_load_dwordx4 v[244:247], v85, s[70:71]
	global_load_dwordx4 v[248:251], v85, s[70:71] offset:64
	v_add_u32_e32 v85, 0x4000, v85
	v_add_u32_e32 v227, 0xf80, v29
	v_cvt_f32_i32_e32 v227, v227
	v_mul_f32_e32 v227, v93, v227
	v_mul_f32_e32 v227, 0x3fb8aa3b, v227
	v_exp_f32_e32 v226, v227
	s_waitcnt lgkmcnt(12)
	v_mfma_f32_16x16x32_f16 v[8:11], v[20:23], v[0:3], 0
	v_mfma_f32_16x16x32_f16 v[8:11], v[24:27], v[4:7], v[8:11]
	s_nop 7
	v_cndmask_b32_e64 v222, v8, v11, s[40:41]
	v_cndmask_b32_e64 v223, v9, v10, s[40:41]
	v_cndmask_b32_e64 v224, v10, v9, s[40:41]
	v_cndmask_b32_e64 v225, v11, v8, s[40:41]
	v_mul_f32_e32 v222, v222, v226
	v_mul_f32_e32 v223, v223, v226
	v_mul_f32_e32 v224, v224, v226
	v_mul_f32_e32 v225, v225, v226
	v_mul_f32_e32 v222, v80, v222
	v_mul_f32_e32 v223, v81, v223
	v_mul_f32_e32 v224, v82, v224
	v_mul_f32_e32 v225, v84, v225
	v_mul_f32_e32 v31, v222, v222
	v_fmac_f32_e32 v31, v223, v223
	v_fmac_f32_e32 v31, v224, v224
	v_fmac_f32_e32 v31, v225, v225
	v_add_f32_e32 v28, v28, v31
	s_mov_b64 exec, s[38:39]
	ds_write_b32 v78, v222
	ds_write_b32 v78, v223 offset:8
	ds_write_b32 v78, v224 offset:16
	ds_write_b32 v78, v225 offset:24
	s_mov_b64 exec, -1
	v_add_u32_e32 v78, v78, v79
	s_waitcnt vmcnt(4)
	ds_bpermute_b32 v20, v30, v228
	ds_bpermute_b32 v21, v30, v229
	ds_bpermute_b32 v22, v30, v230
	ds_bpermute_b32 v23, v30, v231
	ds_bpermute_b32 v24, v30, v232
	ds_bpermute_b32 v25, v30, v233
	ds_bpermute_b32 v26, v30, v234
	ds_bpermute_b32 v27, v30, v235
	global_load_dwordx4 v[228:231], v85, s[70:71]
	global_load_dwordx4 v[232:235], v85, s[70:71] offset:64
	v_add_u32_e32 v85, 0x4000, v85
	v_add_u32_e32 v227, 0x1000, v29
	v_cvt_f32_i32_e32 v227, v227
	v_mul_f32_e32 v227, v93, v227
	v_mul_f32_e32 v227, 0x3fb8aa3b, v227
	v_exp_f32_e32 v226, v227
	s_waitcnt lgkmcnt(12)
	v_mfma_f32_16x16x32_f16 v[8:11], v[12:15], v[0:3], 0
	v_mfma_f32_16x16x32_f16 v[8:11], v[16:19], v[4:7], v[8:11]
	s_nop 7
	v_cndmask_b32_e64 v222, v8, v11, s[40:41]
	v_cndmask_b32_e64 v223, v9, v10, s[40:41]
	v_cndmask_b32_e64 v224, v10, v9, s[40:41]
	v_cndmask_b32_e64 v225, v11, v8, s[40:41]
	v_mul_f32_e32 v222, v222, v226
	v_mul_f32_e32 v223, v223, v226
	v_mul_f32_e32 v224, v224, v226
	v_mul_f32_e32 v225, v225, v226
	v_mul_f32_e32 v222, v80, v222
	v_mul_f32_e32 v223, v81, v223
	v_mul_f32_e32 v224, v82, v224
	v_mul_f32_e32 v225, v84, v225
	v_mul_f32_e32 v31, v222, v222
	v_fmac_f32_e32 v31, v223, v223
	v_fmac_f32_e32 v31, v224, v224
	v_fmac_f32_e32 v31, v225, v225
	v_add_f32_e32 v28, v28, v31
	s_mov_b64 exec, s[38:39]
	ds_write_b32 v78, v222
	ds_write_b32 v78, v223 offset:8
	ds_write_b32 v78, v224 offset:16
	ds_write_b32 v78, v225 offset:24
	s_mov_b64 exec, -1
	v_add_u32_e32 v78, v78, v79
	s_waitcnt vmcnt(4)
	ds_bpermute_b32 v12, v30, v236
	ds_bpermute_b32 v13, v30, v237
	ds_bpermute_b32 v14, v30, v238
	ds_bpermute_b32 v15, v30, v239
	ds_bpermute_b32 v16, v30, v240
	ds_bpermute_b32 v17, v30, v241
	ds_bpermute_b32 v18, v30, v242
	ds_bpermute_b32 v19, v30, v243
	global_load_dwordx4 v[236:239], v85, s[70:71]
	global_load_dwordx4 v[240:243], v85, s[70:71] offset:64
	v_add_u32_e32 v85, 0x4000, v85
	v_add_u32_e32 v227, 0x1080, v29
	v_cvt_f32_i32_e32 v227, v227
	v_mul_f32_e32 v227, v93, v227
	v_mul_f32_e32 v227, 0x3fb8aa3b, v227
	v_exp_f32_e32 v226, v227
	s_waitcnt lgkmcnt(12)
	v_mfma_f32_16x16x32_f16 v[8:11], v[20:23], v[0:3], 0
	v_mfma_f32_16x16x32_f16 v[8:11], v[24:27], v[4:7], v[8:11]
	s_nop 7
	v_cndmask_b32_e64 v222, v8, v11, s[40:41]
	v_cndmask_b32_e64 v223, v9, v10, s[40:41]
	v_cndmask_b32_e64 v224, v10, v9, s[40:41]
	v_cndmask_b32_e64 v225, v11, v8, s[40:41]
	v_mul_f32_e32 v222, v222, v226
	v_mul_f32_e32 v223, v223, v226
	v_mul_f32_e32 v224, v224, v226
	v_mul_f32_e32 v225, v225, v226
	v_mul_f32_e32 v222, v80, v222
	v_mul_f32_e32 v223, v81, v223
	v_mul_f32_e32 v224, v82, v224
	v_mul_f32_e32 v225, v84, v225
	v_mul_f32_e32 v31, v222, v222
	v_fmac_f32_e32 v31, v223, v223
	v_fmac_f32_e32 v31, v224, v224
	v_fmac_f32_e32 v31, v225, v225
	v_add_f32_e32 v28, v28, v31
	s_mov_b64 exec, s[38:39]
	ds_write_b32 v78, v222
	ds_write_b32 v78, v223 offset:8
	ds_write_b32 v78, v224 offset:16
	ds_write_b32 v78, v225 offset:24
	s_mov_b64 exec, -1
	v_add_u32_e32 v78, v78, v79
	s_waitcnt vmcnt(4)
; __device__ __forceinline__ void phase_hyena(KP kp_, int hf){ asm volatile("" : "+s"(kp_)); const Params p=load_params(kp_);
;     ...
;       _Pragma("unroll 8") for (int i=0;i<64;++i){ int tl=wid+8*i;
;         const _Float16* ap=a3+(size_t)(tl*16+n)*64+kg*8;
;         f16x8 a0=*(const f16x8*)ap, a1=*(const f16x8*)(ap+32);
;         f32x4 dd={0.f,0.f,0.f,0.f};
;         dd=__builtin_amdgcn_mfma_f32_16x16x32_f16(a0,bw0,dd,0,0,0);
;         dd=__builtin_amdgcn_mfma_f32_16x16x32_f16(a1,bw1,dd,0,0,0);
;         if (n<4){ float d0=__expf(dsc*(float)(tl*16)); int lag0=tl*16+kg*4;
;           float v0=dd[0]*d0*pj0, v1=dd[1]*d0*pj1, v2=dd[2]*d0*pj2, v3=dd[3]*d0*pj3;
;           if (!side1){ Zf[2*(lag0)+order]=v0; Zf[2*(lag0+1)+order]=v1; Zf[2*(lag0+2)+order]=v2; Zf[2*(lag0+3)+order]=v3; ssl+=v0*v0+v1*v1+v2*v2+v3*v3; }
;           else { if (lag0>=1){ Zf[2*(16384-lag0)+order]=v0; ssl+=v0*v0; }
;             Zf[2*(16384-lag0-1)+order]=v1; Zf[2*(16384-lag0-2)+order]=v2; Zf[2*(16384-lag0-3)+order]=v3; ssl+=v1*v1+v2*v2+v3*v3; } }
;       }
	ds_bpermute_b32 v20, v30, v244
	ds_bpermute_b32 v21, v30, v245
	ds_bpermute_b32 v22, v30, v246
	ds_bpermute_b32 v23, v30, v247
	ds_bpermute_b32 v24, v30, v248
	ds_bpermute_b32 v25, v30, v249
	ds_bpermute_b32 v26, v30, v250
	ds_bpermute_b32 v27, v30, v251
	global_load_dwordx4 v[244:247], v85, s[70:71]
	global_load_dwordx4 v[248:251], v85, s[70:71] offset:64
	v_add_u32_e32 v85, 0x4000, v85
	v_add_u32_e32 v227, 0x1100, v29
	v_cvt_f32_i32_e32 v227, v227
	v_mul_f32_e32 v227, v93, v227
	v_mul_f32_e32 v227, 0x3fb8aa3b, v227
	v_exp_f32_e32 v226, v227
	s_waitcnt lgkmcnt(12)
	v_mfma_f32_16x16x32_f16 v[8:11], v[12:15], v[0:3], 0
	v_mfma_f32_16x16x32_f16 v[8:11], v[16:19], v[4:7], v[8:11]
	s_nop 7
	v_cndmask_b32_e64 v222, v8, v11, s[40:41]
	v_cndmask_b32_e64 v223, v9, v10, s[40:41]
	v_cndmask_b32_e64 v224, v10, v9, s[40:41]
	v_cndmask_b32_e64 v225, v11, v8, s[40:41]
	v_mul_f32_e32 v222, v222, v226
	v_mul_f32_e32 v223, v223, v226
	v_mul_f32_e32 v224, v224, v226
	v_mul_f32_e32 v225, v225, v226
	v_mul_f32_e32 v222, v80, v222
	v_mul_f32_e32 v223, v81, v223
	v_mul_f32_e32 v224, v82, v224
	v_mul_f32_e32 v225, v84, v225
	v_mul_f32_e32 v31, v222, v222
	v_fmac_f32_e32 v31, v223, v223
	v_fmac_f32_e32 v31, v224, v224
	v_fmac_f32_e32 v31, v225, v225
	v_add_f32_e32 v28, v28, v31
	s_mov_b64 exec, s[38:39]
	ds_write_b32 v78, v222
	ds_write_b32 v78, v223 offset:8
	ds_write_b32 v78, v224 offset:16
	ds_write_b32 v78, v225 offset:24
	s_mov_b64 exec, -1
	v_add_u32_e32 v78, v78, v79
	s_waitcnt vmcnt(4)
	ds_bpermute_b32 v12, v30, v228
	ds_bpermute_b32 v13, v30, v229
	ds_bpermute_b32 v14, v30, v230
	ds_bpermute_b32 v15, v30, v231
	ds_bpermute_b32 v16, v30, v232
	ds_bpermute_b32 v17, v30, v233
	ds_bpermute_b32 v18, v30, v234
	ds_bpermute_b32 v19, v30, v235
	global_load_dwordx4 v[228:231], v85, s[70:71]
	global_load_dwordx4 v[232:235], v85, s[70:71] offset:64
	v_add_u32_e32 v85, 0x4000, v85
	v_add_u32_e32 v227, 0x1180, v29
	v_cvt_f32_i32_e32 v227, v227
	v_mul_f32_e32 v227, v93, v227
	v_mul_f32_e32 v227, 0x3fb8aa3b, v227
	v_exp_f32_e32 v226, v227
	s_waitcnt lgkmcnt(12)
	v_mfma_f32_16x16x32_f16 v[8:11], v[20:23], v[0:3], 0
	v_mfma_f32_16x16x32_f16 v[8:11], v[24:27], v[4:7], v[8:11]
	s_nop 7
	v_cndmask_b32_e64 v222, v8, v11, s[40:41]
	v_cndmask_b32_e64 v223, v9, v10, s[40:41]
	v_cndmask_b32_e64 v224, v10, v9, s[40:41]
	v_cndmask_b32_e64 v225, v11, v8, s[40:41]
	v_mul_f32_e32 v222, v222, v226
	v_mul_f32_e32 v223, v223, v226
	v_mul_f32_e32 v224, v224, v226
	v_mul_f32_e32 v225, v225, v226
	v_mul_f32_e32 v222, v80, v222
	v_mul_f32_e32 v223, v81, v223
	v_mul_f32_e32 v224, v82, v224
	v_mul_f32_e32 v225, v84, v225
	v_mul_f32_e32 v31, v222, v222
	v_fmac_f32_e32 v31, v223, v223
	v_fmac_f32_e32 v31, v224, v224
	v_fmac_f32_e32 v31, v225, v225
	v_add_f32_e32 v28, v28, v31
	s_mov_b64 exec, s[38:39]
	ds_write_b32 v78, v222
	ds_write_b32 v78, v223 offset:8
	ds_write_b32 v78, v224 offset:16
	ds_write_b32 v78, v225 offset:24
	s_mov_b64 exec, -1
	v_add_u32_e32 v78, v78, v79
	s_waitcnt vmcnt(4)
	ds_bpermute_b32 v20, v30, v236
	ds_bpermute_b32 v21, v30, v237
	ds_bpermute_b32 v22, v30, v238
	ds_bpermute_b32 v23, v30, v239
	ds_bpermute_b32 v24, v30, v240
	ds_bpermute_b32 v25, v30, v241
	ds_bpermute_b32 v26, v30, v242
	ds_bpermute_b32 v27, v30, v243
	global_load_dwordx4 v[236:239], v85, s[70:71]
	global_load_dwordx4 v[240:243], v85, s[70:71] offset:64
	v_add_u32_e32 v85, 0x4000, v85
	v_add_u32_e32 v227, 0x1200, v29
	v_cvt_f32_i32_e32 v227, v227
	v_mul_f32_e32 v227, v93, v227
	v_mul_f32_e32 v227, 0x3fb8aa3b, v227
	v_exp_f32_e32 v226, v227
	s_waitcnt lgkmcnt(12)
	v_mfma_f32_16x16x32_f16 v[8:11], v[12:15], v[0:3], 0
	v_mfma_f32_16x16x32_f16 v[8:11], v[16:19], v[4:7], v[8:11]
	s_nop 7
	v_cndmask_b32_e64 v222, v8, v11, s[40:41]
	v_cndmask_b32_e64 v223, v9, v10, s[40:41]
	v_cndmask_b32_e64 v224, v10, v9, s[40:41]
	v_cndmask_b32_e64 v225, v11, v8, s[40:41]
	v_mul_f32_e32 v222, v222, v226
	v_mul_f32_e32 v223, v223, v226
	v_mul_f32_e32 v224, v224, v226
	v_mul_f32_e32 v225, v225, v226
	v_mul_f32_e32 v222, v80, v222
	v_mul_f32_e32 v223, v81, v223
	v_mul_f32_e32 v224, v82, v224
	v_mul_f32_e32 v225, v84, v225
	v_mul_f32_e32 v31, v222, v222
	v_fmac_f32_e32 v31, v223, v223
	v_fmac_f32_e32 v31, v224, v224
	v_fmac_f32_e32 v31, v225, v225
	v_add_f32_e32 v28, v28, v31
	s_mov_b64 exec, s[38:39]
	ds_write_b32 v78, v222
	ds_write_b32 v78, v223 offset:8
	ds_write_b32 v78, v224 offset:16
	ds_write_b32 v78, v225 offset:24
	s_mov_b64 exec, -1
	v_add_u32_e32 v78, v78, v79
	s_waitcnt vmcnt(4)
	ds_bpermute_b32 v12, v30, v244
	ds_bpermute_b32 v13, v30, v245
	ds_bpermute_b32 v14, v30, v246
	ds_bpermute_b32 v15, v30, v247
	ds_bpermute_b32 v16, v30, v248
	ds_bpermute_b32 v17, v30, v249
	ds_bpermute_b32 v18, v30, v250
	ds_bpermute_b32 v19, v30, v251
	global_load_dwordx4 v[244:247], v85, s[70:71]
	global_load_dwordx4 v[248:251], v85, s[70:71] offset:64
	v_add_u32_e32 v85, 0x4000, v85
	v_add_u32_e32 v227, 0x1280, v29
	v_cvt_f32_i32_e32 v227, v227
	v_mul_f32_e32 v227, v93, v227
	v_mul_f32_e32 v227, 0x3fb8aa3b, v227
	v_exp_f32_e32 v226, v227
	s_waitcnt lgkmcnt(12)
	v_mfma_f32_16x16x32_f16 v[8:11], v[20:23], v[0:3], 0
	v_mfma_f32_16x16x32_f16 v[8:11], v[24:27], v[4:7], v[8:11]
	s_nop 7
	v_cndmask_b32_e64 v222, v8, v11, s[40:41]
	v_cndmask_b32_e64 v223, v9, v10, s[40:41]
	v_cndmask_b32_e64 v224, v10, v9, s[40:41]
	v_cndmask_b32_e64 v225, v11, v8, s[40:41]
	v_mul_f32_e32 v222, v222, v226
	v_mul_f32_e32 v223, v223, v226
	v_mul_f32_e32 v224, v224, v226
	v_mul_f32_e32 v225, v225, v226
	v_mul_f32_e32 v222, v80, v222
	v_mul_f32_e32 v223, v81, v223
	v_mul_f32_e32 v224, v82, v224
	v_mul_f32_e32 v225, v84, v225
	v_mul_f32_e32 v31, v222, v222
	v_fmac_f32_e32 v31, v223, v223
	v_fmac_f32_e32 v31, v224, v224
	v_fmac_f32_e32 v31, v225, v225
	v_add_f32_e32 v28, v28, v31
	s_mov_b64 exec, s[38:39]
	ds_write_b32 v78, v222
	ds_write_b32 v78, v223 offset:8
	ds_write_b32 v78, v224 offset:16
	ds_write_b32 v78, v225 offset:24
	s_mov_b64 exec, -1
	v_add_u32_e32 v78, v78, v79
	s_waitcnt vmcnt(4)
; __device__ __forceinline__ void phase_hyena(KP kp_, int hf){ asm volatile("" : "+s"(kp_)); const Params p=load_params(kp_);
;     ...
;       _Pragma("unroll 8") for (int i=0;i<64;++i){ int tl=wid+8*i;
;         const _Float16* ap=a3+(size_t)(tl*16+n)*64+kg*8;
;         f16x8 a0=*(const f16x8*)ap, a1=*(const f16x8*)(ap+32);
;         f32x4 dd={0.f,0.f,0.f,0.f};
;         dd=__builtin_amdgcn_mfma_f32_16x16x32_f16(a0,bw0,dd,0,0,0);
;         dd=__builtin_amdgcn_mfma_f32_16x16x32_f16(a1,bw1,dd,0,0,0);
;         if (n<4){ float d0=__expf(dsc*(float)(tl*16)); int lag0=tl*16+kg*4;
;           float v0=dd[0]*d0*pj0, v1=dd[1]*d0*pj1, v2=dd[2]*d0*pj2, v3=dd[3]*d0*pj3;
;           if (!side1){ Zf[2*(lag0)+order]=v0; Zf[2*(lag0+1)+order]=v1; Zf[2*(lag0+2)+order]=v2; Zf[2*(lag0+3)+order]=v3; ssl+=v0*v0+v1*v1+v2*v2+v3*v3; }
;           else { if (lag0>=1){ Zf[2*(16384-lag0)+order]=v0; ssl+=v0*v0; }
;             Zf[2*(16384-lag0-1)+order]=v1; Zf[2*(16384-lag0-2)+order]=v2; Zf[2*(16384-lag0-3)+order]=v3; ssl+=v1*v1+v2*v2+v3*v3; } }
;       }
	ds_bpermute_b32 v20, v30, v228
	ds_bpermute_b32 v21, v30, v229
	ds_bpermute_b32 v22, v30, v230
	ds_bpermute_b32 v23, v30, v231
	ds_bpermute_b32 v24, v30, v232
	ds_bpermute_b32 v25, v30, v233
	ds_bpermute_b32 v26, v30, v234
	ds_bpermute_b32 v27, v30, v235
	global_load_dwordx4 v[228:231], v85, s[70:71]
	global_load_dwordx4 v[232:235], v85, s[70:71] offset:64
	v_add_u32_e32 v85, 0x4000, v85
	v_add_u32_e32 v227, 0x1300, v29
	v_cvt_f32_i32_e32 v227, v227
	v_mul_f32_e32 v227, v93, v227
	v_mul_f32_e32 v227, 0x3fb8aa3b, v227
	v_exp_f32_e32 v226, v227
	s_waitcnt lgkmcnt(12)
	v_mfma_f32_16x16x32_f16 v[8:11], v[12:15], v[0:3], 0
	v_mfma_f32_16x16x32_f16 v[8:11], v[16:19], v[4:7], v[8:11]
	s_nop 7
	v_cndmask_b32_e64 v222, v8, v11, s[40:41]
	v_cndmask_b32_e64 v223, v9, v10, s[40:41]
	v_cndmask_b32_e64 v224, v10, v9, s[40:41]
	v_cndmask_b32_e64 v225, v11, v8, s[40:41]
	v_mul_f32_e32 v222, v222, v226
	v_mul_f32_e32 v223, v223, v226
	v_mul_f32_e32 v224, v224, v226
	v_mul_f32_e32 v225, v225, v226
	v_mul_f32_e32 v222, v80, v222
	v_mul_f32_e32 v223, v81, v223
	v_mul_f32_e32 v224, v82, v224
	v_mul_f32_e32 v225, v84, v225
	v_mul_f32_e32 v31, v222, v222
	v_fmac_f32_e32 v31, v223, v223
	v_fmac_f32_e32 v31, v224, v224
	v_fmac_f32_e32 v31, v225, v225
	v_add_f32_e32 v28, v28, v31
	s_mov_b64 exec, s[38:39]
	ds_write_b32 v78, v222
	ds_write_b32 v78, v223 offset:8
	ds_write_b32 v78, v224 offset:16
	ds_write_b32 v78, v225 offset:24
	s_mov_b64 exec, -1
	v_add_u32_e32 v78, v78, v79
	s_waitcnt vmcnt(4)
	ds_bpermute_b32 v12, v30, v236
	ds_bpermute_b32 v13, v30, v237
	ds_bpermute_b32 v14, v30, v238
	ds_bpermute_b32 v15, v30, v239
	ds_bpermute_b32 v16, v30, v240
	ds_bpermute_b32 v17, v30, v241
	ds_bpermute_b32 v18, v30, v242
	ds_bpermute_b32 v19, v30, v243
	global_load_dwordx4 v[236:239], v85, s[70:71]
	global_load_dwordx4 v[240:243], v85, s[70:71] offset:64
	v_add_u32_e32 v85, 0x4000, v85
	v_add_u32_e32 v227, 0x1380, v29
	v_cvt_f32_i32_e32 v227, v227
	v_mul_f32_e32 v227, v93, v227
	v_mul_f32_e32 v227, 0x3fb8aa3b, v227
	v_exp_f32_e32 v226, v227
	s_waitcnt lgkmcnt(12)
	v_mfma_f32_16x16x32_f16 v[8:11], v[20:23], v[0:3], 0
	v_mfma_f32_16x16x32_f16 v[8:11], v[24:27], v[4:7], v[8:11]
	s_nop 7
	v_cndmask_b32_e64 v222, v8, v11, s[40:41]
	v_cndmask_b32_e64 v223, v9, v10, s[40:41]
	v_cndmask_b32_e64 v224, v10, v9, s[40:41]
	v_cndmask_b32_e64 v225, v11, v8, s[40:41]
	v_mul_f32_e32 v222, v222, v226
	v_mul_f32_e32 v223, v223, v226
	v_mul_f32_e32 v224, v224, v226
	v_mul_f32_e32 v225, v225, v226
	v_mul_f32_e32 v222, v80, v222
	v_mul_f32_e32 v223, v81, v223
	v_mul_f32_e32 v224, v82, v224
	v_mul_f32_e32 v225, v84, v225
	v_mul_f32_e32 v31, v222, v222
	v_fmac_f32_e32 v31, v223, v223
	v_fmac_f32_e32 v31, v224, v224
	v_fmac_f32_e32 v31, v225, v225
	v_add_f32_e32 v28, v28, v31
	s_mov_b64 exec, s[38:39]
	ds_write_b32 v78, v222
	ds_write_b32 v78, v223 offset:8
	ds_write_b32 v78, v224 offset:16
	ds_write_b32 v78, v225 offset:24
	s_mov_b64 exec, -1
	v_add_u32_e32 v78, v78, v79
	s_waitcnt vmcnt(4)
	ds_bpermute_b32 v20, v30, v244
	ds_bpermute_b32 v21, v30, v245
	ds_bpermute_b32 v22, v30, v246
	ds_bpermute_b32 v23, v30, v247
	ds_bpermute_b32 v24, v30, v248
	ds_bpermute_b32 v25, v30, v249
	ds_bpermute_b32 v26, v30, v250
	ds_bpermute_b32 v27, v30, v251
	global_load_dwordx4 v[244:247], v85, s[70:71]
	global_load_dwordx4 v[248:251], v85, s[70:71] offset:64
	v_add_u32_e32 v85, 0x4000, v85
	v_add_u32_e32 v227, 0x1400, v29
	v_cvt_f32_i32_e32 v227, v227
	v_mul_f32_e32 v227, v93, v227
	v_mul_f32_e32 v227, 0x3fb8aa3b, v227
	v_exp_f32_e32 v226, v227
	s_waitcnt lgkmcnt(12)
	v_mfma_f32_16x16x32_f16 v[8:11], v[12:15], v[0:3], 0
	v_mfma_f32_16x16x32_f16 v[8:11], v[16:19], v[4:7], v[8:11]
	s_nop 7
	v_cndmask_b32_e64 v222, v8, v11, s[40:41]
	v_cndmask_b32_e64 v223, v9, v10, s[40:41]
	v_cndmask_b32_e64 v224, v10, v9, s[40:41]
	v_cndmask_b32_e64 v225, v11, v8, s[40:41]
	v_mul_f32_e32 v222, v222, v226
	v_mul_f32_e32 v223, v223, v226
	v_mul_f32_e32 v224, v224, v226
	v_mul_f32_e32 v225, v225, v226
	v_mul_f32_e32 v222, v80, v222
	v_mul_f32_e32 v223, v81, v223
	v_mul_f32_e32 v224, v82, v224
	v_mul_f32_e32 v225, v84, v225
	v_mul_f32_e32 v31, v222, v222
	v_fmac_f32_e32 v31, v223, v223
	v_fmac_f32_e32 v31, v224, v224
	v_fmac_f32_e32 v31, v225, v225
	v_add_f32_e32 v28, v28, v31
	s_mov_b64 exec, s[38:39]
	ds_write_b32 v78, v222
	ds_write_b32 v78, v223 offset:8
	ds_write_b32 v78, v224 offset:16
	ds_write_b32 v78, v225 offset:24
	s_mov_b64 exec, -1
	v_add_u32_e32 v78, v78, v79
	s_waitcnt vmcnt(4)
	ds_bpermute_b32 v12, v30, v228
	ds_bpermute_b32 v13, v30, v229
	ds_bpermute_b32 v14, v30, v230
	ds_bpermute_b32 v15, v30, v231
	ds_bpermute_b32 v16, v30, v232
	ds_bpermute_b32 v17, v30, v233
	ds_bpermute_b32 v18, v30, v234
	ds_bpermute_b32 v19, v30, v235
	global_load_dwordx4 v[228:231], v85, s[70:71]
	global_load_dwordx4 v[232:235], v85, s[70:71] offset:64
	v_add_u32_e32 v85, 0x4000, v85
	v_add_u32_e32 v227, 0x1480, v29
	v_cvt_f32_i32_e32 v227, v227
	v_mul_f32_e32 v227, v93, v227
	v_mul_f32_e32 v227, 0x3fb8aa3b, v227
	v_exp_f32_e32 v226, v227
	s_waitcnt lgkmcnt(12)
	v_mfma_f32_16x16x32_f16 v[8:11], v[20:23], v[0:3], 0
	v_mfma_f32_16x16x32_f16 v[8:11], v[24:27], v[4:7], v[8:11]
	s_nop 7
	v_cndmask_b32_e64 v222, v8, v11, s[40:41]
	v_cndmask_b32_e64 v223, v9, v10, s[40:41]
	v_cndmask_b32_e64 v224, v10, v9, s[40:41]
	v_cndmask_b32_e64 v225, v11, v8, s[40:41]
	v_mul_f32_e32 v222, v222, v226
	v_mul_f32_e32 v223, v223, v226
	v_mul_f32_e32 v224, v224, v226
	v_mul_f32_e32 v225, v225, v226
	v_mul_f32_e32 v222, v80, v222
	v_mul_f32_e32 v223, v81, v223
	v_mul_f32_e32 v224, v82, v224
	v_mul_f32_e32 v225, v84, v225
	v_mul_f32_e32 v31, v222, v222
	v_fmac_f32_e32 v31, v223, v223
	v_fmac_f32_e32 v31, v224, v224
	v_fmac_f32_e32 v31, v225, v225
	v_add_f32_e32 v28, v28, v31
	s_mov_b64 exec, s[38:39]
	ds_write_b32 v78, v222
	ds_write_b32 v78, v223 offset:8
	ds_write_b32 v78, v224 offset:16
	ds_write_b32 v78, v225 offset:24
	s_mov_b64 exec, -1
	v_add_u32_e32 v78, v78, v79
	s_waitcnt vmcnt(4)
; __device__ __forceinline__ void phase_hyena(KP kp_, int hf){ asm volatile("" : "+s"(kp_)); const Params p=load_params(kp_);
;     ...
;       _Pragma("unroll 8") for (int i=0;i<64;++i){ int tl=wid+8*i;
;         const _Float16* ap=a3+(size_t)(tl*16+n)*64+kg*8;
;         f16x8 a0=*(const f16x8*)ap, a1=*(const f16x8*)(ap+32);
;         f32x4 dd={0.f,0.f,0.f,0.f};
;         dd=__builtin_amdgcn_mfma_f32_16x16x32_f16(a0,bw0,dd,0,0,0);
;         dd=__builtin_amdgcn_mfma_f32_16x16x32_f16(a1,bw1,dd,0,0,0);
;         if (n<4){ float d0=__expf(dsc*(float)(tl*16)); int lag0=tl*16+kg*4;
;           float v0=dd[0]*d0*pj0, v1=dd[1]*d0*pj1, v2=dd[2]*d0*pj2, v3=dd[3]*d0*pj3;
;           if (!side1){ Zf[2*(lag0)+order]=v0; Zf[2*(lag0+1)+order]=v1; Zf[2*(lag0+2)+order]=v2; Zf[2*(lag0+3)+order]=v3; ssl+=v0*v0+v1*v1+v2*v2+v3*v3; }
;           else { if (lag0>=1){ Zf[2*(16384-lag0)+order]=v0; ssl+=v0*v0; }
;             Zf[2*(16384-lag0-1)+order]=v1; Zf[2*(16384-lag0-2)+order]=v2; Zf[2*(16384-lag0-3)+order]=v3; ssl+=v1*v1+v2*v2+v3*v3; } }
;       }
	ds_bpermute_b32 v20, v30, v236
	ds_bpermute_b32 v21, v30, v237
	ds_bpermute_b32 v22, v30, v238
	ds_bpermute_b32 v23, v30, v239
	ds_bpermute_b32 v24, v30, v240
	ds_bpermute_b32 v25, v30, v241
	ds_bpermute_b32 v26, v30, v242
	ds_bpermute_b32 v27, v30, v243
	global_load_dwordx4 v[236:239], v85, s[70:71]
	global_load_dwordx4 v[240:243], v85, s[70:71] offset:64
	v_add_u32_e32 v85, 0x4000, v85
	v_add_u32_e32 v227, 0x1500, v29
	v_cvt_f32_i32_e32 v227, v227
	v_mul_f32_e32 v227, v93, v227
	v_mul_f32_e32 v227, 0x3fb8aa3b, v227
	v_exp_f32_e32 v226, v227
	s_waitcnt lgkmcnt(12)
	v_mfma_f32_16x16x32_f16 v[8:11], v[12:15], v[0:3], 0
	v_mfma_f32_16x16x32_f16 v[8:11], v[16:19], v[4:7], v[8:11]
	s_nop 7
	v_cndmask_b32_e64 v222, v8, v11, s[40:41]
	v_cndmask_b32_e64 v223, v9, v10, s[40:41]
	v_cndmask_b32_e64 v224, v10, v9, s[40:41]
	v_cndmask_b32_e64 v225, v11, v8, s[40:41]
	v_mul_f32_e32 v222, v222, v226
	v_mul_f32_e32 v223, v223, v226
	v_mul_f32_e32 v224, v224, v226
	v_mul_f32_e32 v225, v225, v226
	v_mul_f32_e32 v222, v80, v222
	v_mul_f32_e32 v223, v81, v223
	v_mul_f32_e32 v224, v82, v224
	v_mul_f32_e32 v225, v84, v225
	v_mul_f32_e32 v31, v222, v222
	v_fmac_f32_e32 v31, v223, v223
	v_fmac_f32_e32 v31, v224, v224
	v_fmac_f32_e32 v31, v225, v225
	v_add_f32_e32 v28, v28, v31
	s_mov_b64 exec, s[38:39]
	ds_write_b32 v78, v222
	ds_write_b32 v78, v223 offset:8
	ds_write_b32 v78, v224 offset:16
	ds_write_b32 v78, v225 offset:24
	s_mov_b64 exec, -1
	v_add_u32_e32 v78, v78, v79
	s_waitcnt vmcnt(4)
	ds_bpermute_b32 v12, v30, v244
	ds_bpermute_b32 v13, v30, v245
	ds_bpermute_b32 v14, v30, v246
	ds_bpermute_b32 v15, v30, v247
	ds_bpermute_b32 v16, v30, v248
	ds_bpermute_b32 v17, v30, v249
	ds_bpermute_b32 v18, v30, v250
	ds_bpermute_b32 v19, v30, v251
	global_load_dwordx4 v[244:247], v85, s[70:71]
	global_load_dwordx4 v[248:251], v85, s[70:71] offset:64
	v_add_u32_e32 v85, 0x4000, v85
	v_add_u32_e32 v227, 0x1580, v29
	v_cvt_f32_i32_e32 v227, v227
	v_mul_f32_e32 v227, v93, v227
	v_mul_f32_e32 v227, 0x3fb8aa3b, v227
	v_exp_f32_e32 v226, v227
	s_waitcnt lgkmcnt(12)
	v_mfma_f32_16x16x32_f16 v[8:11], v[20:23], v[0:3], 0
	v_mfma_f32_16x16x32_f16 v[8:11], v[24:27], v[4:7], v[8:11]
	s_nop 7
	v_cndmask_b32_e64 v222, v8, v11, s[40:41]
	v_cndmask_b32_e64 v223, v9, v10, s[40:41]
	v_cndmask_b32_e64 v224, v10, v9, s[40:41]
	v_cndmask_b32_e64 v225, v11, v8, s[40:41]
	v_mul_f32_e32 v222, v222, v226
	v_mul_f32_e32 v223, v223, v226
	v_mul_f32_e32 v224, v224, v226
	v_mul_f32_e32 v225, v225, v226
	v_mul_f32_e32 v222, v80, v222
	v_mul_f32_e32 v223, v81, v223
	v_mul_f32_e32 v224, v82, v224
	v_mul_f32_e32 v225, v84, v225
	v_mul_f32_e32 v31, v222, v222
	v_fmac_f32_e32 v31, v223, v223
	v_fmac_f32_e32 v31, v224, v224
	v_fmac_f32_e32 v31, v225, v225
	v_add_f32_e32 v28, v28, v31
	s_mov_b64 exec, s[38:39]
	ds_write_b32 v78, v222
	ds_write_b32 v78, v223 offset:8
	ds_write_b32 v78, v224 offset:16
	ds_write_b32 v78, v225 offset:24
	s_mov_b64 exec, -1
	v_add_u32_e32 v78, v78, v79
	s_waitcnt vmcnt(4)
	ds_bpermute_b32 v20, v30, v228
	ds_bpermute_b32 v21, v30, v229
	ds_bpermute_b32 v22, v30, v230
	ds_bpermute_b32 v23, v30, v231
	ds_bpermute_b32 v24, v30, v232
	ds_bpermute_b32 v25, v30, v233
	ds_bpermute_b32 v26, v30, v234
	ds_bpermute_b32 v27, v30, v235
	global_load_dwordx4 v[228:231], v85, s[70:71]
	global_load_dwordx4 v[232:235], v85, s[70:71] offset:64
	v_add_u32_e32 v85, 0x4000, v85
	v_add_u32_e32 v227, 0x1600, v29
	v_cvt_f32_i32_e32 v227, v227
	v_mul_f32_e32 v227, v93, v227
	v_mul_f32_e32 v227, 0x3fb8aa3b, v227
	v_exp_f32_e32 v226, v227
	s_waitcnt lgkmcnt(12)
	v_mfma_f32_16x16x32_f16 v[8:11], v[12:15], v[0:3], 0
	v_mfma_f32_16x16x32_f16 v[8:11], v[16:19], v[4:7], v[8:11]
	s_nop 7
	v_cndmask_b32_e64 v222, v8, v11, s[40:41]
	v_cndmask_b32_e64 v223, v9, v10, s[40:41]
	v_cndmask_b32_e64 v224, v10, v9, s[40:41]
	v_cndmask_b32_e64 v225, v11, v8, s[40:41]
	v_mul_f32_e32 v222, v222, v226
	v_mul_f32_e32 v223, v223, v226
	v_mul_f32_e32 v224, v224, v226
	v_mul_f32_e32 v225, v225, v226
	v_mul_f32_e32 v222, v80, v222
	v_mul_f32_e32 v223, v81, v223
	v_mul_f32_e32 v224, v82, v224
	v_mul_f32_e32 v225, v84, v225
	v_mul_f32_e32 v31, v222, v222
	v_fmac_f32_e32 v31, v223, v223
	v_fmac_f32_e32 v31, v224, v224
	v_fmac_f32_e32 v31, v225, v225
	v_add_f32_e32 v28, v28, v31
	s_mov_b64 exec, s[38:39]
	ds_write_b32 v78, v222
	ds_write_b32 v78, v223 offset:8
	ds_write_b32 v78, v224 offset:16
	ds_write_b32 v78, v225 offset:24
	s_mov_b64 exec, -1
	v_add_u32_e32 v78, v78, v79
	s_waitcnt vmcnt(4)
	ds_bpermute_b32 v12, v30, v236
	ds_bpermute_b32 v13, v30, v237
	ds_bpermute_b32 v14, v30, v238
	ds_bpermute_b32 v15, v30, v239
	ds_bpermute_b32 v16, v30, v240
	ds_bpermute_b32 v17, v30, v241
	ds_bpermute_b32 v18, v30, v242
	ds_bpermute_b32 v19, v30, v243
	global_load_dwordx4 v[236:239], v85, s[70:71]
	global_load_dwordx4 v[240:243], v85, s[70:71] offset:64
	v_add_u32_e32 v85, 0x4000, v85
	v_add_u32_e32 v227, 0x1680, v29
	v_cvt_f32_i32_e32 v227, v227
	v_mul_f32_e32 v227, v93, v227
	v_mul_f32_e32 v227, 0x3fb8aa3b, v227
	v_exp_f32_e32 v226, v227
	s_waitcnt lgkmcnt(12)
	v_mfma_f32_16x16x32_f16 v[8:11], v[20:23], v[0:3], 0
	v_mfma_f32_16x16x32_f16 v[8:11], v[24:27], v[4:7], v[8:11]
	s_nop 7
	v_cndmask_b32_e64 v222, v8, v11, s[40:41]
	v_cndmask_b32_e64 v223, v9, v10, s[40:41]
	v_cndmask_b32_e64 v224, v10, v9, s[40:41]
	v_cndmask_b32_e64 v225, v11, v8, s[40:41]
	v_mul_f32_e32 v222, v222, v226
	v_mul_f32_e32 v223, v223, v226
	v_mul_f32_e32 v224, v224, v226
	v_mul_f32_e32 v225, v225, v226
	v_mul_f32_e32 v222, v80, v222
	v_mul_f32_e32 v223, v81, v223
	v_mul_f32_e32 v224, v82, v224
	v_mul_f32_e32 v225, v84, v225
	v_mul_f32_e32 v31, v222, v222
	v_fmac_f32_e32 v31, v223, v223
	v_fmac_f32_e32 v31, v224, v224
	v_fmac_f32_e32 v31, v225, v225
	v_add_f32_e32 v28, v28, v31
	s_mov_b64 exec, s[38:39]
	ds_write_b32 v78, v222
	ds_write_b32 v78, v223 offset:8
	ds_write_b32 v78, v224 offset:16
	ds_write_b32 v78, v225 offset:24
	s_mov_b64 exec, -1
	v_add_u32_e32 v78, v78, v79
	s_waitcnt vmcnt(4)
; __device__ __forceinline__ void phase_hyena(KP kp_, int hf){ asm volatile("" : "+s"(kp_)); const Params p=load_params(kp_);
;     ...
;       _Pragma("unroll 8") for (int i=0;i<64;++i){ int tl=wid+8*i;
;         const _Float16* ap=a3+(size_t)(tl*16+n)*64+kg*8;
;         f16x8 a0=*(const f16x8*)ap, a1=*(const f16x8*)(ap+32);
;         f32x4 dd={0.f,0.f,0.f,0.f};
;         dd=__builtin_amdgcn_mfma_f32_16x16x32_f16(a0,bw0,dd,0,0,0);
;         dd=__builtin_amdgcn_mfma_f32_16x16x32_f16(a1,bw1,dd,0,0,0);
;         if (n<4){ float d0=__expf(dsc*(float)(tl*16)); int lag0=tl*16+kg*4;
;           float v0=dd[0]*d0*pj0, v1=dd[1]*d0*pj1, v2=dd[2]*d0*pj2, v3=dd[3]*d0*pj3;
;           if (!side1){ Zf[2*(lag0)+order]=v0; Zf[2*(lag0+1)+order]=v1; Zf[2*(lag0+2)+order]=v2; Zf[2*(lag0+3)+order]=v3; ssl+=v0*v0+v1*v1+v2*v2+v3*v3; }
;           else { if (lag0>=1){ Zf[2*(16384-lag0)+order]=v0; ssl+=v0*v0; }
;             Zf[2*(16384-lag0-1)+order]=v1; Zf[2*(16384-lag0-2)+order]=v2; Zf[2*(16384-lag0-3)+order]=v3; ssl+=v1*v1+v2*v2+v3*v3; } }
;       }
	ds_bpermute_b32 v20, v30, v244
	ds_bpermute_b32 v21, v30, v245
	ds_bpermute_b32 v22, v30, v246
	ds_bpermute_b32 v23, v30, v247
	ds_bpermute_b32 v24, v30, v248
	ds_bpermute_b32 v25, v30, v249
	ds_bpermute_b32 v26, v30, v250
	ds_bpermute_b32 v27, v30, v251
	global_load_dwordx4 v[244:247], v85, s[70:71]
	global_load_dwordx4 v[248:251], v85, s[70:71] offset:64
	v_add_u32_e32 v85, 0x4000, v85
	v_add_u32_e32 v227, 0x1700, v29
	v_cvt_f32_i32_e32 v227, v227
	v_mul_f32_e32 v227, v93, v227
	v_mul_f32_e32 v227, 0x3fb8aa3b, v227
	v_exp_f32_e32 v226, v227
	s_waitcnt lgkmcnt(12)
	v_mfma_f32_16x16x32_f16 v[8:11], v[12:15], v[0:3], 0
	v_mfma_f32_16x16x32_f16 v[8:11], v[16:19], v[4:7], v[8:11]
	s_nop 7
	v_cndmask_b32_e64 v222, v8, v11, s[40:41]
	v_cndmask_b32_e64 v223, v9, v10, s[40:41]
	v_cndmask_b32_e64 v224, v10, v9, s[40:41]
	v_cndmask_b32_e64 v225, v11, v8, s[40:41]
	v_mul_f32_e32 v222, v222, v226
	v_mul_f32_e32 v223, v223, v226
	v_mul_f32_e32 v224, v224, v226
	v_mul_f32_e32 v225, v225, v226
	v_mul_f32_e32 v222, v80, v222
	v_mul_f32_e32 v223, v81, v223
	v_mul_f32_e32 v224, v82, v224
	v_mul_f32_e32 v225, v84, v225
	v_mul_f32_e32 v31, v222, v222
	v_fmac_f32_e32 v31, v223, v223
	v_fmac_f32_e32 v31, v224, v224
	v_fmac_f32_e32 v31, v225, v225
	v_add_f32_e32 v28, v28, v31
	s_mov_b64 exec, s[38:39]
	ds_write_b32 v78, v222
	ds_write_b32 v78, v223 offset:8
	ds_write_b32 v78, v224 offset:16
	ds_write_b32 v78, v225 offset:24
	s_mov_b64 exec, -1
	v_add_u32_e32 v78, v78, v79
	s_waitcnt vmcnt(4)
	ds_bpermute_b32 v12, v30, v228
	ds_bpermute_b32 v13, v30, v229
	ds_bpermute_b32 v14, v30, v230
	ds_bpermute_b32 v15, v30, v231
	ds_bpermute_b32 v16, v30, v232
	ds_bpermute_b32 v17, v30, v233
	ds_bpermute_b32 v18, v30, v234
	ds_bpermute_b32 v19, v30, v235
	global_load_dwordx4 v[228:231], v85, s[70:71]
	global_load_dwordx4 v[232:235], v85, s[70:71] offset:64
	v_add_u32_e32 v85, 0x4000, v85
	v_add_u32_e32 v227, 0x1780, v29
	v_cvt_f32_i32_e32 v227, v227
	v_mul_f32_e32 v227, v93, v227
	v_mul_f32_e32 v227, 0x3fb8aa3b, v227
	v_exp_f32_e32 v226, v227
	s_waitcnt lgkmcnt(12)
	v_mfma_f32_16x16x32_f16 v[8:11], v[20:23], v[0:3], 0
	v_mfma_f32_16x16x32_f16 v[8:11], v[24:27], v[4:7], v[8:11]
	s_nop 7
	v_cndmask_b32_e64 v222, v8, v11, s[40:41]
	v_cndmask_b32_e64 v223, v9, v10, s[40:41]
	v_cndmask_b32_e64 v224, v10, v9, s[40:41]
	v_cndmask_b32_e64 v225, v11, v8, s[40:41]
	v_mul_f32_e32 v222, v222, v226
	v_mul_f32_e32 v223, v223, v226
	v_mul_f32_e32 v224, v224, v226
	v_mul_f32_e32 v225, v225, v226
	v_mul_f32_e32 v222, v80, v222
	v_mul_f32_e32 v223, v81, v223
	v_mul_f32_e32 v224, v82, v224
	v_mul_f32_e32 v225, v84, v225
	v_mul_f32_e32 v31, v222, v222
	v_fmac_f32_e32 v31, v223, v223
	v_fmac_f32_e32 v31, v224, v224
	v_fmac_f32_e32 v31, v225, v225
	v_add_f32_e32 v28, v28, v31
	s_mov_b64 exec, s[38:39]
	ds_write_b32 v78, v222
	ds_write_b32 v78, v223 offset:8
	ds_write_b32 v78, v224 offset:16
	ds_write_b32 v78, v225 offset:24
	s_mov_b64 exec, -1
	v_add_u32_e32 v78, v78, v79
	s_waitcnt vmcnt(4)
	ds_bpermute_b32 v20, v30, v236
	ds_bpermute_b32 v21, v30, v237
	ds_bpermute_b32 v22, v30, v238
	ds_bpermute_b32 v23, v30, v239
	ds_bpermute_b32 v24, v30, v240
	ds_bpermute_b32 v25, v30, v241
	ds_bpermute_b32 v26, v30, v242
	ds_bpermute_b32 v27, v30, v243
	global_load_dwordx4 v[236:239], v85, s[70:71]
	global_load_dwordx4 v[240:243], v85, s[70:71] offset:64
	v_add_u32_e32 v85, 0x4000, v85
	v_add_u32_e32 v227, 0x1800, v29
	v_cvt_f32_i32_e32 v227, v227
	v_mul_f32_e32 v227, v93, v227
	v_mul_f32_e32 v227, 0x3fb8aa3b, v227
	v_exp_f32_e32 v226, v227
	s_waitcnt lgkmcnt(12)
	v_mfma_f32_16x16x32_f16 v[8:11], v[12:15], v[0:3], 0
	v_mfma_f32_16x16x32_f16 v[8:11], v[16:19], v[4:7], v[8:11]
	s_nop 7
	v_cndmask_b32_e64 v222, v8, v11, s[40:41]
	v_cndmask_b32_e64 v223, v9, v10, s[40:41]
	v_cndmask_b32_e64 v224, v10, v9, s[40:41]
	v_cndmask_b32_e64 v225, v11, v8, s[40:41]
	v_mul_f32_e32 v222, v222, v226
	v_mul_f32_e32 v223, v223, v226
	v_mul_f32_e32 v224, v224, v226
	v_mul_f32_e32 v225, v225, v226
	v_mul_f32_e32 v222, v80, v222
	v_mul_f32_e32 v223, v81, v223
	v_mul_f32_e32 v224, v82, v224
	v_mul_f32_e32 v225, v84, v225
	v_mul_f32_e32 v31, v222, v222
	v_fmac_f32_e32 v31, v223, v223
	v_fmac_f32_e32 v31, v224, v224
	v_fmac_f32_e32 v31, v225, v225
	v_add_f32_e32 v28, v28, v31
	s_mov_b64 exec, s[38:39]
	ds_write_b32 v78, v222
	ds_write_b32 v78, v223 offset:8
	ds_write_b32 v78, v224 offset:16
	ds_write_b32 v78, v225 offset:24
	s_mov_b64 exec, -1
	v_add_u32_e32 v78, v78, v79
	s_waitcnt vmcnt(4)
	ds_bpermute_b32 v12, v30, v244
	ds_bpermute_b32 v13, v30, v245
	ds_bpermute_b32 v14, v30, v246
	ds_bpermute_b32 v15, v30, v247
	ds_bpermute_b32 v16, v30, v248
	ds_bpermute_b32 v17, v30, v249
	ds_bpermute_b32 v18, v30, v250
	ds_bpermute_b32 v19, v30, v251
	global_load_dwordx4 v[244:247], v85, s[70:71]
	global_load_dwordx4 v[248:251], v85, s[70:71] offset:64
	v_add_u32_e32 v85, 0x4000, v85
	v_add_u32_e32 v227, 0x1880, v29
	v_cvt_f32_i32_e32 v227, v227
	v_mul_f32_e32 v227, v93, v227
	v_mul_f32_e32 v227, 0x3fb8aa3b, v227
	v_exp_f32_e32 v226, v227
	s_waitcnt lgkmcnt(12)
	v_mfma_f32_16x16x32_f16 v[8:11], v[20:23], v[0:3], 0
	v_mfma_f32_16x16x32_f16 v[8:11], v[24:27], v[4:7], v[8:11]
	s_nop 7
	v_cndmask_b32_e64 v222, v8, v11, s[40:41]
	v_cndmask_b32_e64 v223, v9, v10, s[40:41]
	v_cndmask_b32_e64 v224, v10, v9, s[40:41]
	v_cndmask_b32_e64 v225, v11, v8, s[40:41]
	v_mul_f32_e32 v222, v222, v226
	v_mul_f32_e32 v223, v223, v226
	v_mul_f32_e32 v224, v224, v226
	v_mul_f32_e32 v225, v225, v226
	v_mul_f32_e32 v222, v80, v222
	v_mul_f32_e32 v223, v81, v223
	v_mul_f32_e32 v224, v82, v224
	v_mul_f32_e32 v225, v84, v225
	v_mul_f32_e32 v31, v222, v222
	v_fmac_f32_e32 v31, v223, v223
	v_fmac_f32_e32 v31, v224, v224
	v_fmac_f32_e32 v31, v225, v225
	v_add_f32_e32 v28, v28, v31
	s_mov_b64 exec, s[38:39]
	ds_write_b32 v78, v222
	ds_write_b32 v78, v223 offset:8
	ds_write_b32 v78, v224 offset:16
	ds_write_b32 v78, v225 offset:24
	s_mov_b64 exec, -1
	v_add_u32_e32 v78, v78, v79
	s_waitcnt vmcnt(4)
; __device__ __forceinline__ void phase_hyena(KP kp_, int hf){ asm volatile("" : "+s"(kp_)); const Params p=load_params(kp_);
;     ...
;       _Pragma("unroll 8") for (int i=0;i<64;++i){ int tl=wid+8*i;
;         const _Float16* ap=a3+(size_t)(tl*16+n)*64+kg*8;
;         f16x8 a0=*(const f16x8*)ap, a1=*(const f16x8*)(ap+32);
;         f32x4 dd={0.f,0.f,0.f,0.f};
;         dd=__builtin_amdgcn_mfma_f32_16x16x32_f16(a0,bw0,dd,0,0,0);
;         dd=__builtin_amdgcn_mfma_f32_16x16x32_f16(a1,bw1,dd,0,0,0);
;         if (n<4){ float d0=__expf(dsc*(float)(tl*16)); int lag0=tl*16+kg*4;
;           float v0=dd[0]*d0*pj0, v1=dd[1]*d0*pj1, v2=dd[2]*d0*pj2, v3=dd[3]*d0*pj3;
;           if (!side1){ Zf[2*(lag0)+order]=v0; Zf[2*(lag0+1)+order]=v1; Zf[2*(lag0+2)+order]=v2; Zf[2*(lag0+3)+order]=v3; ssl+=v0*v0+v1*v1+v2*v2+v3*v3; }
;           else { if (lag0>=1){ Zf[2*(16384-lag0)+order]=v0; ssl+=v0*v0; }
;             Zf[2*(16384-lag0-1)+order]=v1; Zf[2*(16384-lag0-2)+order]=v2; Zf[2*(16384-lag0-3)+order]=v3; ssl+=v1*v1+v2*v2+v3*v3; } }
;       }
	ds_bpermute_b32 v20, v30, v228
	ds_bpermute_b32 v21, v30, v229
	ds_bpermute_b32 v22, v30, v230
	ds_bpermute_b32 v23, v30, v231
	ds_bpermute_b32 v24, v30, v232
	ds_bpermute_b32 v25, v30, v233
	ds_bpermute_b32 v26, v30, v234
	ds_bpermute_b32 v27, v30, v235
	global_load_dwordx4 v[228:231], v85, s[70:71]
	global_load_dwordx4 v[232:235], v85, s[70:71] offset:64
	v_add_u32_e32 v85, 0x4000, v85
	v_add_u32_e32 v227, 0x1900, v29
	v_cvt_f32_i32_e32 v227, v227
	v_mul_f32_e32 v227, v93, v227
	v_mul_f32_e32 v227, 0x3fb8aa3b, v227
	v_exp_f32_e32 v226, v227
	s_waitcnt lgkmcnt(12)
	v_mfma_f32_16x16x32_f16 v[8:11], v[12:15], v[0:3], 0
	v_mfma_f32_16x16x32_f16 v[8:11], v[16:19], v[4:7], v[8:11]
	s_nop 7
	v_cndmask_b32_e64 v222, v8, v11, s[40:41]
	v_cndmask_b32_e64 v223, v9, v10, s[40:41]
	v_cndmask_b32_e64 v224, v10, v9, s[40:41]
	v_cndmask_b32_e64 v225, v11, v8, s[40:41]
	v_mul_f32_e32 v222, v222, v226
	v_mul_f32_e32 v223, v223, v226
	v_mul_f32_e32 v224, v224, v226
	v_mul_f32_e32 v225, v225, v226
	v_mul_f32_e32 v222, v80, v222
	v_mul_f32_e32 v223, v81, v223
	v_mul_f32_e32 v224, v82, v224
	v_mul_f32_e32 v225, v84, v225
	v_mul_f32_e32 v31, v222, v222
	v_fmac_f32_e32 v31, v223, v223
	v_fmac_f32_e32 v31, v224, v224
	v_fmac_f32_e32 v31, v225, v225
	v_add_f32_e32 v28, v28, v31
	s_mov_b64 exec, s[38:39]
	ds_write_b32 v78, v222
	ds_write_b32 v78, v223 offset:8
	ds_write_b32 v78, v224 offset:16
	ds_write_b32 v78, v225 offset:24
	s_mov_b64 exec, -1
	v_add_u32_e32 v78, v78, v79
	s_waitcnt vmcnt(4)
	ds_bpermute_b32 v12, v30, v236
	ds_bpermute_b32 v13, v30, v237
	ds_bpermute_b32 v14, v30, v238
	ds_bpermute_b32 v15, v30, v239
	ds_bpermute_b32 v16, v30, v240
	ds_bpermute_b32 v17, v30, v241
	ds_bpermute_b32 v18, v30, v242
	ds_bpermute_b32 v19, v30, v243
	global_load_dwordx4 v[236:239], v85, s[70:71]
	global_load_dwordx4 v[240:243], v85, s[70:71] offset:64
	v_add_u32_e32 v85, 0x4000, v85
	v_add_u32_e32 v227, 0x1980, v29
	v_cvt_f32_i32_e32 v227, v227
	v_mul_f32_e32 v227, v93, v227
	v_mul_f32_e32 v227, 0x3fb8aa3b, v227
	v_exp_f32_e32 v226, v227
	s_waitcnt lgkmcnt(12)
	v_mfma_f32_16x16x32_f16 v[8:11], v[20:23], v[0:3], 0
	v_mfma_f32_16x16x32_f16 v[8:11], v[24:27], v[4:7], v[8:11]
	s_nop 7
	v_cndmask_b32_e64 v222, v8, v11, s[40:41]
	v_cndmask_b32_e64 v223, v9, v10, s[40:41]
	v_cndmask_b32_e64 v224, v10, v9, s[40:41]
	v_cndmask_b32_e64 v225, v11, v8, s[40:41]
	v_mul_f32_e32 v222, v222, v226
	v_mul_f32_e32 v223, v223, v226
	v_mul_f32_e32 v224, v224, v226
	v_mul_f32_e32 v225, v225, v226
	v_mul_f32_e32 v222, v80, v222
	v_mul_f32_e32 v223, v81, v223
	v_mul_f32_e32 v224, v82, v224
	v_mul_f32_e32 v225, v84, v225
	v_mul_f32_e32 v31, v222, v222
	v_fmac_f32_e32 v31, v223, v223
	v_fmac_f32_e32 v31, v224, v224
	v_fmac_f32_e32 v31, v225, v225
	v_add_f32_e32 v28, v28, v31
	s_mov_b64 exec, s[38:39]
	ds_write_b32 v78, v222
	ds_write_b32 v78, v223 offset:8
	ds_write_b32 v78, v224 offset:16
	ds_write_b32 v78, v225 offset:24
	s_mov_b64 exec, -1
	v_add_u32_e32 v78, v78, v79
	s_waitcnt vmcnt(4)
	ds_bpermute_b32 v20, v30, v244
	ds_bpermute_b32 v21, v30, v245
	ds_bpermute_b32 v22, v30, v246
	ds_bpermute_b32 v23, v30, v247
	ds_bpermute_b32 v24, v30, v248
	ds_bpermute_b32 v25, v30, v249
	ds_bpermute_b32 v26, v30, v250
	ds_bpermute_b32 v27, v30, v251
	global_load_dwordx4 v[244:247], v85, s[70:71]
	global_load_dwordx4 v[248:251], v85, s[70:71] offset:64
	v_add_u32_e32 v85, 0x4000, v85
	v_add_u32_e32 v227, 0x1a00, v29
	v_cvt_f32_i32_e32 v227, v227
	v_mul_f32_e32 v227, v93, v227
	v_mul_f32_e32 v227, 0x3fb8aa3b, v227
	v_exp_f32_e32 v226, v227
	s_waitcnt lgkmcnt(12)
	v_mfma_f32_16x16x32_f16 v[8:11], v[12:15], v[0:3], 0
	v_mfma_f32_16x16x32_f16 v[8:11], v[16:19], v[4:7], v[8:11]
	s_nop 7
	v_cndmask_b32_e64 v222, v8, v11, s[40:41]
	v_cndmask_b32_e64 v223, v9, v10, s[40:41]
	v_cndmask_b32_e64 v224, v10, v9, s[40:41]
	v_cndmask_b32_e64 v225, v11, v8, s[40:41]
	v_mul_f32_e32 v222, v222, v226
	v_mul_f32_e32 v223, v223, v226
	v_mul_f32_e32 v224, v224, v226
	v_mul_f32_e32 v225, v225, v226
	v_mul_f32_e32 v222, v80, v222
	v_mul_f32_e32 v223, v81, v223
	v_mul_f32_e32 v224, v82, v224
	v_mul_f32_e32 v225, v84, v225
	v_mul_f32_e32 v31, v222, v222
	v_fmac_f32_e32 v31, v223, v223
	v_fmac_f32_e32 v31, v224, v224
	v_fmac_f32_e32 v31, v225, v225
	v_add_f32_e32 v28, v28, v31
	s_mov_b64 exec, s[38:39]
	ds_write_b32 v78, v222
	ds_write_b32 v78, v223 offset:8
	ds_write_b32 v78, v224 offset:16
	ds_write_b32 v78, v225 offset:24
	s_mov_b64 exec, -1
	v_add_u32_e32 v78, v78, v79
	s_waitcnt vmcnt(4)
	ds_bpermute_b32 v12, v30, v228
	ds_bpermute_b32 v13, v30, v229
	ds_bpermute_b32 v14, v30, v230
	ds_bpermute_b32 v15, v30, v231
	ds_bpermute_b32 v16, v30, v232
	ds_bpermute_b32 v17, v30, v233
	ds_bpermute_b32 v18, v30, v234
	ds_bpermute_b32 v19, v30, v235
	global_load_dwordx4 v[228:231], v85, s[70:71]
	global_load_dwordx4 v[232:235], v85, s[70:71] offset:64
	v_add_u32_e32 v85, 0x4000, v85
	v_add_u32_e32 v227, 0x1a80, v29
	v_cvt_f32_i32_e32 v227, v227
	v_mul_f32_e32 v227, v93, v227
	v_mul_f32_e32 v227, 0x3fb8aa3b, v227
	v_exp_f32_e32 v226, v227
	s_waitcnt lgkmcnt(12)
	v_mfma_f32_16x16x32_f16 v[8:11], v[20:23], v[0:3], 0
	v_mfma_f32_16x16x32_f16 v[8:11], v[24:27], v[4:7], v[8:11]
	s_nop 7
	v_cndmask_b32_e64 v222, v8, v11, s[40:41]
	v_cndmask_b32_e64 v223, v9, v10, s[40:41]
	v_cndmask_b32_e64 v224, v10, v9, s[40:41]
	v_cndmask_b32_e64 v225, v11, v8, s[40:41]
	v_mul_f32_e32 v222, v222, v226
	v_mul_f32_e32 v223, v223, v226
	v_mul_f32_e32 v224, v224, v226
	v_mul_f32_e32 v225, v225, v226
	v_mul_f32_e32 v222, v80, v222
	v_mul_f32_e32 v223, v81, v223
	v_mul_f32_e32 v224, v82, v224
	v_mul_f32_e32 v225, v84, v225
	v_mul_f32_e32 v31, v222, v222
	v_fmac_f32_e32 v31, v223, v223
	v_fmac_f32_e32 v31, v224, v224
	v_fmac_f32_e32 v31, v225, v225
	v_add_f32_e32 v28, v28, v31
	s_mov_b64 exec, s[38:39]
	ds_write_b32 v78, v222
	ds_write_b32 v78, v223 offset:8
	ds_write_b32 v78, v224 offset:16
	ds_write_b32 v78, v225 offset:24
	s_mov_b64 exec, -1
	v_add_u32_e32 v78, v78, v79
	s_waitcnt vmcnt(4)
; __device__ __forceinline__ void phase_hyena(KP kp_, int hf){ asm volatile("" : "+s"(kp_)); const Params p=load_params(kp_);
;     ...
;       _Pragma("unroll 8") for (int i=0;i<64;++i){ int tl=wid+8*i;
;         const _Float16* ap=a3+(size_t)(tl*16+n)*64+kg*8;
;         f16x8 a0=*(const f16x8*)ap, a1=*(const f16x8*)(ap+32);
;         f32x4 dd={0.f,0.f,0.f,0.f};
;         dd=__builtin_amdgcn_mfma_f32_16x16x32_f16(a0,bw0,dd,0,0,0);
;         dd=__builtin_amdgcn_mfma_f32_16x16x32_f16(a1,bw1,dd,0,0,0);
;         if (n<4){ float d0=__expf(dsc*(float)(tl*16)); int lag0=tl*16+kg*4;
;           float v0=dd[0]*d0*pj0, v1=dd[1]*d0*pj1, v2=dd[2]*d0*pj2, v3=dd[3]*d0*pj3;
;           if (!side1){ Zf[2*(lag0)+order]=v0; Zf[2*(lag0+1)+order]=v1; Zf[2*(lag0+2)+order]=v2; Zf[2*(lag0+3)+order]=v3; ssl+=v0*v0+v1*v1+v2*v2+v3*v3; }
;           else { if (lag0>=1){ Zf[2*(16384-lag0)+order]=v0; ssl+=v0*v0; }
;             Zf[2*(16384-lag0-1)+order]=v1; Zf[2*(16384-lag0-2)+order]=v2; Zf[2*(16384-lag0-3)+order]=v3; ssl+=v1*v1+v2*v2+v3*v3; } }
;       }
	ds_bpermute_b32 v20, v30, v236
	ds_bpermute_b32 v21, v30, v237
	ds_bpermute_b32 v22, v30, v238
	ds_bpermute_b32 v23, v30, v239
	ds_bpermute_b32 v24, v30, v240
	ds_bpermute_b32 v25, v30, v241
	ds_bpermute_b32 v26, v30, v242
	ds_bpermute_b32 v27, v30, v243
	global_load_dwordx4 v[236:239], v85, s[70:71]
	global_load_dwordx4 v[240:243], v85, s[70:71] offset:64
	v_add_u32_e32 v85, 0x4000, v85
	v_add_u32_e32 v227, 0x1b00, v29
	v_cvt_f32_i32_e32 v227, v227
	v_mul_f32_e32 v227, v93, v227
	v_mul_f32_e32 v227, 0x3fb8aa3b, v227
	v_exp_f32_e32 v226, v227
	s_waitcnt lgkmcnt(12)
	v_mfma_f32_16x16x32_f16 v[8:11], v[12:15], v[0:3], 0
	v_mfma_f32_16x16x32_f16 v[8:11], v[16:19], v[4:7], v[8:11]
	s_nop 7
	v_cndmask_b32_e64 v222, v8, v11, s[40:41]
	v_cndmask_b32_e64 v223, v9, v10, s[40:41]
	v_cndmask_b32_e64 v224, v10, v9, s[40:41]
	v_cndmask_b32_e64 v225, v11, v8, s[40:41]
	v_mul_f32_e32 v222, v222, v226
	v_mul_f32_e32 v223, v223, v226
	v_mul_f32_e32 v224, v224, v226
	v_mul_f32_e32 v225, v225, v226
	v_mul_f32_e32 v222, v80, v222
	v_mul_f32_e32 v223, v81, v223
	v_mul_f32_e32 v224, v82, v224
	v_mul_f32_e32 v225, v84, v225
	v_mul_f32_e32 v31, v222, v222
	v_fmac_f32_e32 v31, v223, v223
	v_fmac_f32_e32 v31, v224, v224
	v_fmac_f32_e32 v31, v225, v225
	v_add_f32_e32 v28, v28, v31
	s_mov_b64 exec, s[38:39]
	ds_write_b32 v78, v222
	ds_write_b32 v78, v223 offset:8
	ds_write_b32 v78, v224 offset:16
	ds_write_b32 v78, v225 offset:24
	s_mov_b64 exec, -1
	v_add_u32_e32 v78, v78, v79
	s_waitcnt vmcnt(4)
	ds_bpermute_b32 v12, v30, v244
	ds_bpermute_b32 v13, v30, v245
	ds_bpermute_b32 v14, v30, v246
	ds_bpermute_b32 v15, v30, v247
	ds_bpermute_b32 v16, v30, v248
	ds_bpermute_b32 v17, v30, v249
	ds_bpermute_b32 v18, v30, v250
	ds_bpermute_b32 v19, v30, v251
	global_load_dwordx4 v[244:247], v85, s[70:71]
	global_load_dwordx4 v[248:251], v85, s[70:71] offset:64
	v_add_u32_e32 v85, 0x4000, v85
	v_add_u32_e32 v227, 0x1b80, v29
	v_cvt_f32_i32_e32 v227, v227
	v_mul_f32_e32 v227, v93, v227
	v_mul_f32_e32 v227, 0x3fb8aa3b, v227
	v_exp_f32_e32 v226, v227
	s_waitcnt lgkmcnt(12)
	v_mfma_f32_16x16x32_f16 v[8:11], v[20:23], v[0:3], 0
	v_mfma_f32_16x16x32_f16 v[8:11], v[24:27], v[4:7], v[8:11]
	s_nop 7
	v_cndmask_b32_e64 v222, v8, v11, s[40:41]
	v_cndmask_b32_e64 v223, v9, v10, s[40:41]
	v_cndmask_b32_e64 v224, v10, v9, s[40:41]
	v_cndmask_b32_e64 v225, v11, v8, s[40:41]
	v_mul_f32_e32 v222, v222, v226
	v_mul_f32_e32 v223, v223, v226
	v_mul_f32_e32 v224, v224, v226
	v_mul_f32_e32 v225, v225, v226
	v_mul_f32_e32 v222, v80, v222
	v_mul_f32_e32 v223, v81, v223
	v_mul_f32_e32 v224, v82, v224
	v_mul_f32_e32 v225, v84, v225
	v_mul_f32_e32 v31, v222, v222
	v_fmac_f32_e32 v31, v223, v223
	v_fmac_f32_e32 v31, v224, v224
	v_fmac_f32_e32 v31, v225, v225
	v_add_f32_e32 v28, v28, v31
	s_mov_b64 exec, s[38:39]
	ds_write_b32 v78, v222
	ds_write_b32 v78, v223 offset:8
	ds_write_b32 v78, v224 offset:16
	ds_write_b32 v78, v225 offset:24
	s_mov_b64 exec, -1
	v_add_u32_e32 v78, v78, v79
	s_waitcnt vmcnt(4)
	ds_bpermute_b32 v20, v30, v228
	ds_bpermute_b32 v21, v30, v229
	ds_bpermute_b32 v22, v30, v230
	ds_bpermute_b32 v23, v30, v231
	ds_bpermute_b32 v24, v30, v232
	ds_bpermute_b32 v25, v30, v233
	ds_bpermute_b32 v26, v30, v234
	ds_bpermute_b32 v27, v30, v235
	global_load_dwordx4 v[228:231], v85, s[70:71]
	global_load_dwordx4 v[232:235], v85, s[70:71] offset:64
	v_add_u32_e32 v85, 0x4000, v85
	v_add_u32_e32 v227, 0x1c00, v29
	v_cvt_f32_i32_e32 v227, v227
	v_mul_f32_e32 v227, v93, v227
	v_mul_f32_e32 v227, 0x3fb8aa3b, v227
	v_exp_f32_e32 v226, v227
	s_waitcnt lgkmcnt(12)
	v_mfma_f32_16x16x32_f16 v[8:11], v[12:15], v[0:3], 0
	v_mfma_f32_16x16x32_f16 v[8:11], v[16:19], v[4:7], v[8:11]
	s_nop 7
	v_cndmask_b32_e64 v222, v8, v11, s[40:41]
	v_cndmask_b32_e64 v223, v9, v10, s[40:41]
	v_cndmask_b32_e64 v224, v10, v9, s[40:41]
	v_cndmask_b32_e64 v225, v11, v8, s[40:41]
	v_mul_f32_e32 v222, v222, v226
	v_mul_f32_e32 v223, v223, v226
	v_mul_f32_e32 v224, v224, v226
	v_mul_f32_e32 v225, v225, v226
	v_mul_f32_e32 v222, v80, v222
	v_mul_f32_e32 v223, v81, v223
	v_mul_f32_e32 v224, v82, v224
	v_mul_f32_e32 v225, v84, v225
	v_mul_f32_e32 v31, v222, v222
	v_fmac_f32_e32 v31, v223, v223
	v_fmac_f32_e32 v31, v224, v224
	v_fmac_f32_e32 v31, v225, v225
	v_add_f32_e32 v28, v28, v31
	s_mov_b64 exec, s[38:39]
	ds_write_b32 v78, v222
	ds_write_b32 v78, v223 offset:8
	ds_write_b32 v78, v224 offset:16
	ds_write_b32 v78, v225 offset:24
	s_mov_b64 exec, -1
	v_add_u32_e32 v78, v78, v79
	s_waitcnt vmcnt(4)
	ds_bpermute_b32 v12, v30, v236
	ds_bpermute_b32 v13, v30, v237
	ds_bpermute_b32 v14, v30, v238
	ds_bpermute_b32 v15, v30, v239
	ds_bpermute_b32 v16, v30, v240
	ds_bpermute_b32 v17, v30, v241
	ds_bpermute_b32 v18, v30, v242
	ds_bpermute_b32 v19, v30, v243
	global_load_dwordx4 v[236:239], v85, s[70:71]
	global_load_dwordx4 v[240:243], v85, s[70:71] offset:64
	v_add_u32_e32 v85, 0x4000, v85
	v_add_u32_e32 v227, 0x1c80, v29
	v_cvt_f32_i32_e32 v227, v227
	v_mul_f32_e32 v227, v93, v227
	v_mul_f32_e32 v227, 0x3fb8aa3b, v227
	v_exp_f32_e32 v226, v227
	s_waitcnt lgkmcnt(12)
	v_mfma_f32_16x16x32_f16 v[8:11], v[20:23], v[0:3], 0
	v_mfma_f32_16x16x32_f16 v[8:11], v[24:27], v[4:7], v[8:11]
	s_nop 7
	v_cndmask_b32_e64 v222, v8, v11, s[40:41]
	v_cndmask_b32_e64 v223, v9, v10, s[40:41]
	v_cndmask_b32_e64 v224, v10, v9, s[40:41]
	v_cndmask_b32_e64 v225, v11, v8, s[40:41]
	v_mul_f32_e32 v222, v222, v226
	v_mul_f32_e32 v223, v223, v226
	v_mul_f32_e32 v224, v224, v226
	v_mul_f32_e32 v225, v225, v226
	v_mul_f32_e32 v222, v80, v222
	v_mul_f32_e32 v223, v81, v223
	v_mul_f32_e32 v224, v82, v224
	v_mul_f32_e32 v225, v84, v225
	v_mul_f32_e32 v31, v222, v222
	v_fmac_f32_e32 v31, v223, v223
	v_fmac_f32_e32 v31, v224, v224
	v_fmac_f32_e32 v31, v225, v225
	v_add_f32_e32 v28, v28, v31
	s_mov_b64 exec, s[38:39]
	ds_write_b32 v78, v222
	ds_write_b32 v78, v223 offset:8
	ds_write_b32 v78, v224 offset:16
	ds_write_b32 v78, v225 offset:24
	s_mov_b64 exec, -1
	v_add_u32_e32 v78, v78, v79
	s_waitcnt vmcnt(4)
; __device__ __forceinline__ void phase_hyena(KP kp_, int hf){ asm volatile("" : "+s"(kp_)); const Params p=load_params(kp_);
;     ...
;       _Pragma("unroll 8") for (int i=0;i<64;++i){ int tl=wid+8*i;
;         const _Float16* ap=a3+(size_t)(tl*16+n)*64+kg*8;
;         f16x8 a0=*(const f16x8*)ap, a1=*(const f16x8*)(ap+32);
;         f32x4 dd={0.f,0.f,0.f,0.f};
;         dd=__builtin_amdgcn_mfma_f32_16x16x32_f16(a0,bw0,dd,0,0,0);
;         dd=__builtin_amdgcn_mfma_f32_16x16x32_f16(a1,bw1,dd,0,0,0);
;         if (n<4){ float d0=__expf(dsc*(float)(tl*16)); int lag0=tl*16+kg*4;
;           float v0=dd[0]*d0*pj0, v1=dd[1]*d0*pj1, v2=dd[2]*d0*pj2, v3=dd[3]*d0*pj3;
;           if (!side1){ Zf[2*(lag0)+order]=v0; Zf[2*(lag0+1)+order]=v1; Zf[2*(lag0+2)+order]=v2; Zf[2*(lag0+3)+order]=v3; ssl+=v0*v0+v1*v1+v2*v2+v3*v3; }
;           else { if (lag0>=1){ Zf[2*(16384-lag0)+order]=v0; ssl+=v0*v0; }
;             Zf[2*(16384-lag0-1)+order]=v1; Zf[2*(16384-lag0-2)+order]=v2; Zf[2*(16384-lag0-3)+order]=v3; ssl+=v1*v1+v2*v2+v3*v3; } }
;       }
	ds_bpermute_b32 v20, v30, v244
	ds_bpermute_b32 v21, v30, v245
	ds_bpermute_b32 v22, v30, v246
	ds_bpermute_b32 v23, v30, v247
	ds_bpermute_b32 v24, v30, v248
	ds_bpermute_b32 v25, v30, v249
	ds_bpermute_b32 v26, v30, v250
	ds_bpermute_b32 v27, v30, v251
	global_load_dwordx4 v[244:247], v85, s[70:71]
	global_load_dwordx4 v[248:251], v85, s[70:71] offset:64
	v_add_u32_e32 v85, 0x4000, v85
	v_add_u32_e32 v227, 0x1d00, v29
	v_cvt_f32_i32_e32 v227, v227
	v_mul_f32_e32 v227, v93, v227
	v_mul_f32_e32 v227, 0x3fb8aa3b, v227
	v_exp_f32_e32 v226, v227
	s_waitcnt lgkmcnt(12)
	v_mfma_f32_16x16x32_f16 v[8:11], v[12:15], v[0:3], 0
	v_mfma_f32_16x16x32_f16 v[8:11], v[16:19], v[4:7], v[8:11]
	s_nop 7
	v_cndmask_b32_e64 v222, v8, v11, s[40:41]
	v_cndmask_b32_e64 v223, v9, v10, s[40:41]
	v_cndmask_b32_e64 v224, v10, v9, s[40:41]
	v_cndmask_b32_e64 v225, v11, v8, s[40:41]
	v_mul_f32_e32 v222, v222, v226
	v_mul_f32_e32 v223, v223, v226
	v_mul_f32_e32 v224, v224, v226
	v_mul_f32_e32 v225, v225, v226
	v_mul_f32_e32 v222, v80, v222
	v_mul_f32_e32 v223, v81, v223
	v_mul_f32_e32 v224, v82, v224
	v_mul_f32_e32 v225, v84, v225
	v_mul_f32_e32 v31, v222, v222
	v_fmac_f32_e32 v31, v223, v223
	v_fmac_f32_e32 v31, v224, v224
	v_fmac_f32_e32 v31, v225, v225
	v_add_f32_e32 v28, v28, v31
	s_mov_b64 exec, s[38:39]
	ds_write_b32 v78, v222
	ds_write_b32 v78, v223 offset:8
	ds_write_b32 v78, v224 offset:16
	ds_write_b32 v78, v225 offset:24
	s_mov_b64 exec, -1
	v_add_u32_e32 v78, v78, v79
	s_waitcnt vmcnt(4)
	ds_bpermute_b32 v12, v30, v228
	ds_bpermute_b32 v13, v30, v229
	ds_bpermute_b32 v14, v30, v230
	ds_bpermute_b32 v15, v30, v231
	ds_bpermute_b32 v16, v30, v232
	ds_bpermute_b32 v17, v30, v233
	ds_bpermute_b32 v18, v30, v234
	ds_bpermute_b32 v19, v30, v235
	global_load_dwordx4 v[228:231], v85, s[70:71]
	global_load_dwordx4 v[232:235], v85, s[70:71] offset:64
	v_add_u32_e32 v85, 0x4000, v85
	v_add_u32_e32 v227, 0x1d80, v29
	v_cvt_f32_i32_e32 v227, v227
	v_mul_f32_e32 v227, v93, v227
	v_mul_f32_e32 v227, 0x3fb8aa3b, v227
	v_exp_f32_e32 v226, v227
	s_waitcnt lgkmcnt(12)
	v_mfma_f32_16x16x32_f16 v[8:11], v[20:23], v[0:3], 0
	v_mfma_f32_16x16x32_f16 v[8:11], v[24:27], v[4:7], v[8:11]
	s_nop 7
	v_cndmask_b32_e64 v222, v8, v11, s[40:41]
	v_cndmask_b32_e64 v223, v9, v10, s[40:41]
	v_cndmask_b32_e64 v224, v10, v9, s[40:41]
	v_cndmask_b32_e64 v225, v11, v8, s[40:41]
	v_mul_f32_e32 v222, v222, v226
	v_mul_f32_e32 v223, v223, v226
	v_mul_f32_e32 v224, v224, v226
	v_mul_f32_e32 v225, v225, v226
	v_mul_f32_e32 v222, v80, v222
	v_mul_f32_e32 v223, v81, v223
	v_mul_f32_e32 v224, v82, v224
	v_mul_f32_e32 v225, v84, v225
	v_mul_f32_e32 v31, v222, v222
	v_fmac_f32_e32 v31, v223, v223
	v_fmac_f32_e32 v31, v224, v224
	v_fmac_f32_e32 v31, v225, v225
	v_add_f32_e32 v28, v28, v31
	s_mov_b64 exec, s[38:39]
	ds_write_b32 v78, v222
	ds_write_b32 v78, v223 offset:8
	ds_write_b32 v78, v224 offset:16
	ds_write_b32 v78, v225 offset:24
	s_mov_b64 exec, -1
	v_add_u32_e32 v78, v78, v79
	s_waitcnt vmcnt(4)
	ds_bpermute_b32 v20, v30, v236
	ds_bpermute_b32 v21, v30, v237
	ds_bpermute_b32 v22, v30, v238
	ds_bpermute_b32 v23, v30, v239
	ds_bpermute_b32 v24, v30, v240
	ds_bpermute_b32 v25, v30, v241
	ds_bpermute_b32 v26, v30, v242
	ds_bpermute_b32 v27, v30, v243
	v_add_u32_e32 v227, 0x1e00, v29
	v_cvt_f32_i32_e32 v227, v227
	v_mul_f32_e32 v227, v93, v227
	v_mul_f32_e32 v227, 0x3fb8aa3b, v227
	v_exp_f32_e32 v226, v227
	s_waitcnt lgkmcnt(12)
	v_mfma_f32_16x16x32_f16 v[8:11], v[12:15], v[0:3], 0
	v_mfma_f32_16x16x32_f16 v[8:11], v[16:19], v[4:7], v[8:11]
	s_nop 7
	v_cndmask_b32_e64 v222, v8, v11, s[40:41]
	v_cndmask_b32_e64 v223, v9, v10, s[40:41]
	v_cndmask_b32_e64 v224, v10, v9, s[40:41]
	v_cndmask_b32_e64 v225, v11, v8, s[40:41]
	v_mul_f32_e32 v222, v222, v226
	v_mul_f32_e32 v223, v223, v226
	v_mul_f32_e32 v224, v224, v226
	v_mul_f32_e32 v225, v225, v226
	v_mul_f32_e32 v222, v80, v222
	v_mul_f32_e32 v223, v81, v223
	v_mul_f32_e32 v224, v82, v224
	v_mul_f32_e32 v225, v84, v225
	v_mul_f32_e32 v31, v222, v222
	v_fmac_f32_e32 v31, v223, v223
	v_fmac_f32_e32 v31, v224, v224
	v_fmac_f32_e32 v31, v225, v225
	v_add_f32_e32 v28, v28, v31
	s_mov_b64 exec, s[38:39]
	ds_write_b32 v78, v222
	ds_write_b32 v78, v223 offset:8
	ds_write_b32 v78, v224 offset:16
	ds_write_b32 v78, v225 offset:24
	s_mov_b64 exec, -1
	v_add_u32_e32 v78, v78, v79
	s_waitcnt vmcnt(2)
; __device__ __forceinline__ void phase_hyena(KP kp_, int hf){ asm volatile("" : "+s"(kp_)); const Params p=load_params(kp_);
;     ...
;       _Pragma("unroll 8") for (int i=0;i<64;++i){ int tl=wid+8*i;
;         const _Float16* ap=a3+(size_t)(tl*16+n)*64+kg*8;
;         f16x8 a0=*(const f16x8*)ap, a1=*(const f16x8*)(ap+32);
;         f32x4 dd={0.f,0.f,0.f,0.f};
;         dd=__builtin_amdgcn_mfma_f32_16x16x32_f16(a0,bw0,dd,0,0,0);
;         dd=__builtin_amdgcn_mfma_f32_16x16x32_f16(a1,bw1,dd,0,0,0);
;         if (n<4){ float d0=__expf(dsc*(float)(tl*16)); int lag0=tl*16+kg*4;
;           float v0=dd[0]*d0*pj0, v1=dd[1]*d0*pj1, v2=dd[2]*d0*pj2, v3=dd[3]*d0*pj3;
;           if (!side1){ Zf[2*(lag0)+order]=v0; Zf[2*(lag0+1)+order]=v1; Zf[2*(lag0+2)+order]=v2; Zf[2*(lag0+3)+order]=v3; ssl+=v0*v0+v1*v1+v2*v2+v3*v3; }
;           else { if (lag0>=1){ Zf[2*(16384-lag0)+order]=v0; ssl+=v0*v0; }
;             Zf[2*(16384-lag0-1)+order]=v1; Zf[2*(16384-lag0-2)+order]=v2; Zf[2*(16384-lag0-3)+order]=v3; ssl+=v1*v1+v2*v2+v3*v3; } }
;       }
;       ss0=(n<4 && order==0)?ssl:0.f; ss1=(n<4 && order==1)?ssl:0.f;
;     }
;     if (tid==0) Z[8192]=make_float2(0.f,0.f);
	ds_bpermute_b32 v12, v30, v244
	ds_bpermute_b32 v13, v30, v245
	ds_bpermute_b32 v14, v30, v246
	ds_bpermute_b32 v15, v30, v247
	ds_bpermute_b32 v16, v30, v248
	ds_bpermute_b32 v17, v30, v249
	ds_bpermute_b32 v18, v30, v250
	ds_bpermute_b32 v19, v30, v251
	v_add_u32_e32 v227, 0x1e80, v29
	v_cvt_f32_i32_e32 v227, v227
	v_mul_f32_e32 v227, v93, v227
	v_mul_f32_e32 v227, 0x3fb8aa3b, v227
	v_exp_f32_e32 v226, v227
	s_waitcnt lgkmcnt(12)
	v_mfma_f32_16x16x32_f16 v[8:11], v[20:23], v[0:3], 0
	v_mfma_f32_16x16x32_f16 v[8:11], v[24:27], v[4:7], v[8:11]
	s_nop 7
	v_cndmask_b32_e64 v222, v8, v11, s[40:41]
	v_cndmask_b32_e64 v223, v9, v10, s[40:41]
	v_cndmask_b32_e64 v224, v10, v9, s[40:41]
	v_cndmask_b32_e64 v225, v11, v8, s[40:41]
	v_mul_f32_e32 v222, v222, v226
	v_mul_f32_e32 v223, v223, v226
	v_mul_f32_e32 v224, v224, v226
	v_mul_f32_e32 v225, v225, v226
	v_mul_f32_e32 v222, v80, v222
	v_mul_f32_e32 v223, v81, v223
	v_mul_f32_e32 v224, v82, v224
	v_mul_f32_e32 v225, v84, v225
	v_mul_f32_e32 v31, v222, v222
	v_fmac_f32_e32 v31, v223, v223
	v_fmac_f32_e32 v31, v224, v224
	v_fmac_f32_e32 v31, v225, v225
	v_add_f32_e32 v28, v28, v31
	s_mov_b64 exec, s[38:39]
	ds_write_b32 v78, v222
	ds_write_b32 v78, v223 offset:8
	ds_write_b32 v78, v224 offset:16
	ds_write_b32 v78, v225 offset:24
	s_mov_b64 exec, -1
	v_add_u32_e32 v78, v78, v79
	s_waitcnt vmcnt(0)
	ds_bpermute_b32 v20, v30, v228
	ds_bpermute_b32 v21, v30, v229
	ds_bpermute_b32 v22, v30, v230
	ds_bpermute_b32 v23, v30, v231
	ds_bpermute_b32 v24, v30, v232
	ds_bpermute_b32 v25, v30, v233
	ds_bpermute_b32 v26, v30, v234
	ds_bpermute_b32 v27, v30, v235
	v_add_u32_e32 v227, 0x1f00, v29
	v_cvt_f32_i32_e32 v227, v227
	v_mul_f32_e32 v227, v93, v227
	v_mul_f32_e32 v227, 0x3fb8aa3b, v227
	v_exp_f32_e32 v226, v227
	s_waitcnt lgkmcnt(12)
	v_mfma_f32_16x16x32_f16 v[8:11], v[12:15], v[0:3], 0
	v_mfma_f32_16x16x32_f16 v[8:11], v[16:19], v[4:7], v[8:11]
	s_nop 7
	v_cndmask_b32_e64 v222, v8, v11, s[40:41]
	v_cndmask_b32_e64 v223, v9, v10, s[40:41]
	v_cndmask_b32_e64 v224, v10, v9, s[40:41]
	v_cndmask_b32_e64 v225, v11, v8, s[40:41]
	v_mul_f32_e32 v222, v222, v226
	v_mul_f32_e32 v223, v223, v226
	v_mul_f32_e32 v224, v224, v226
	v_mul_f32_e32 v225, v225, v226
	v_mul_f32_e32 v222, v80, v222
	v_mul_f32_e32 v223, v81, v223
	v_mul_f32_e32 v224, v82, v224
	v_mul_f32_e32 v225, v84, v225
	v_mul_f32_e32 v31, v222, v222
	v_fmac_f32_e32 v31, v223, v223
	v_fmac_f32_e32 v31, v224, v224
	v_fmac_f32_e32 v31, v225, v225
	v_add_f32_e32 v28, v28, v31
	s_mov_b64 exec, s[38:39]
	ds_write_b32 v78, v222
	ds_write_b32 v78, v223 offset:8
	ds_write_b32 v78, v224 offset:16
	ds_write_b32 v78, v225 offset:24
	s_mov_b64 exec, -1
	v_add_u32_e32 v78, v78, v79
	v_add_u32_e32 v227, 0x1f80, v29
	v_cvt_f32_i32_e32 v227, v227
	v_mul_f32_e32 v227, v93, v227
	v_mul_f32_e32 v227, 0x3fb8aa3b, v227
	v_exp_f32_e32 v226, v227
	s_waitcnt lgkmcnt(4)
	v_mfma_f32_16x16x32_f16 v[8:11], v[20:23], v[0:3], 0
	v_mfma_f32_16x16x32_f16 v[8:11], v[24:27], v[4:7], v[8:11]
	s_nop 7
	v_cndmask_b32_e64 v222, v8, v11, s[40:41]
	v_cndmask_b32_e64 v223, v9, v10, s[40:41]
	v_cndmask_b32_e64 v224, v10, v9, s[40:41]
	v_cndmask_b32_e64 v225, v11, v8, s[40:41]
	v_mul_f32_e32 v222, v222, v226
	v_mul_f32_e32 v223, v223, v226
	v_mul_f32_e32 v224, v224, v226
	v_mul_f32_e32 v225, v225, v226
	v_mul_f32_e32 v222, v80, v222
	v_mul_f32_e32 v223, v81, v223
	v_mul_f32_e32 v224, v82, v224
	v_mul_f32_e32 v225, v84, v225
	v_mul_f32_e32 v31, v222, v222
	v_fmac_f32_e32 v31, v223, v223
	v_fmac_f32_e32 v31, v224, v224
	v_fmac_f32_e32 v31, v225, v225
	v_add_f32_e32 v28, v28, v31
	s_mov_b64 exec, s[38:39]
	ds_write_b32 v78, v222
	ds_write_b32 v78, v223 offset:8
	ds_write_b32 v78, v224 offset:16
	ds_write_b32 v78, v225 offset:24
	s_mov_b64 exec, -1
	v_add_u32_e32 v78, v78, v79
	s_waitcnt lgkmcnt(0)
	s_and_saveexec_b64 s[12:13], s[46:47]
	s_cbranch_execz .LBB0_1316
	v_readlane_b32 s18, v253, 23
	s_nop 1
	v_mov_b32_e32 v0, s18
	ds_write_b64 v0, v[220:221]
